# SB weights: half-wave exchange via v_permlane32_swap instead of ds_bpermute round trips (lever 7: permlane for intra-wave movement)
# speedup vs baseline: 1.0015x; 1.0015x over previous
.LBB0_514:
	v_ashrrev_i32_e32 v6, 4, v147
	v_ashrrev_i32_e32 v7, 31, v6
	v_lshlrev_b64 v[2:3], 13, v[6:7]
	v_lshl_add_u64 v[2:3], v[144:145], 0, v[2:3]
	s_mov_b32 s4, 0x40000
	s_mov_b32 s5, 0
	v_mad_u32_u24 v6, v6, s11, v146
	global_load_dwordx4 v[48:51], v[2:3], off
	v_lshl_add_u64 v[2:3], v[2:3], 0, s[4:5]
	global_load_dwordx4 v[52:55], v[2:3], off
	v_lshl_add_u64 v[2:3], v[2:3], 0, s[4:5]
	global_load_dwordx4 v[56:59], v[2:3], off
	v_lshl_add_u64 v[2:3], v[2:3], 0, s[4:5]
	global_load_dwordx4 v[60:63], v[2:3], off
	v_lshl_add_u64 v[2:3], v[2:3], 0, s[4:5]
	global_load_dwordx4 v[64:67], v[2:3], off
	v_lshl_add_u64 v[2:3], v[2:3], 0, s[4:5]
	global_load_dwordx4 v[68:71], v[2:3], off
	v_lshl_add_u64 v[2:3], v[2:3], 0, s[4:5]
	global_load_dwordx4 v[72:75], v[2:3], off
	v_lshl_add_u64 v[2:3], v[2:3], 0, s[4:5]
	global_load_dwordx4 v[76:79], v[2:3], off
	s_waitcnt vmcnt(7)
	ds_write_b128 v6, v[48:51]
	s_waitcnt vmcnt(6)
	ds_write_b128 v6, v[52:55] offset:8704
	s_waitcnt vmcnt(5)
	ds_write_b128 v6, v[56:59] offset:17408
	s_waitcnt vmcnt(4)
	ds_write_b128 v6, v[60:63] offset:26112
	s_waitcnt vmcnt(3)
	ds_write_b128 v6, v[64:67] offset:34816
	s_waitcnt vmcnt(2)
	ds_write_b128 v6, v[68:71] offset:43520
	s_waitcnt vmcnt(1)
	ds_write_b128 v6, v[72:75] offset:52224
	s_waitcnt vmcnt(0)
	ds_write_b128 v6, v[76:79] offset:60928
	s_movk_i32 s3, 0x1000
	s_lshl_b32 s9, s1, 1
	s_add_u32 s92, s96, s9
	s_addc_u32 s93, s97, 0
	s_add_u32 s40, s29, s9
	s_addc_u32 s41, s80, 0
	s_ashr_i32 s4, s0, 6
	v_and_b32_e32 v205, 31, v147
	s_lshl_b32 s26, s4, 5
	v_or_b32_e32 v1, s26, v205
	v_bfe_u32 v149, v147, 5, 1
	v_mul_lo_u32 v1, v1, s11
	s_lshl_b32 s3, s6, 8
	v_add_u32_e32 v151, 0, v1
	v_lshlrev_b32_e32 v180, 4, v149
	v_add_u32_e32 v1, v151, v180
	v_ashrrev_i32_e32 v182, 4, v147
	s_or_b32 s5, s3, 0xc0
	s_waitcnt lgkmcnt(0)
	s_barrier
	ds_read_b128 v[96:99], v1
	ds_read_b128 v[100:103], v1 offset:32
	ds_read_b128 v[104:107], v1 offset:64
	ds_read_b128 v[108:111], v1 offset:96
	ds_read_b128 v[112:115], v1 offset:128
	ds_read_b128 v[116:119], v1 offset:160
	ds_read_b128 v[120:123], v1 offset:192
	ds_read_b128 v[124:127], v1 offset:224
	v_add_u32_e32 v1, s5, v182
	v_add_u32_e32 v10, 32, v1
	v_mad_i64_i32 v[2:3], s[0:1], v1, s91, 0
	v_mad_i64_i32 v[10:11], s[0:1], v10, s91, 0
	v_or_b32_e32 v2, v2, v148
	v_or_b32_e32 v10, v10, v148
	v_lshlrev_b64 v[2:3], 1, v[2:3]
	v_lshlrev_b64 v[10:11], 1, v[10:11]
	v_lshl_add_u64 v[4:5], s[92:93], 0, v[2:3]
	v_lshl_add_u64 v[6:7], s[40:41], 0, v[2:3]
	v_lshl_add_u64 v[12:13], s[92:93], 0, v[10:11]
	v_lshl_add_u64 v[14:15], s[40:41], 0, v[10:11]
	s_waitcnt lgkmcnt(0)
	s_barrier
	global_load_dwordx4 v[2:5], v[4:5], off
	s_nop 0
	global_load_dwordx4 v[6:9], v[6:7], off
	s_nop 0
	global_load_dwordx4 v[10:13], v[12:13], off
	s_nop 0
	global_load_dwordx4 v[14:17], v[14:15], off
	s_movk_i32 s0, 0x140
	v_subrev_u32_e32 v18, 64, v1
	v_mul_lo_u32 v184, v182, s0
	v_subrev_u32_e32 v1, 32, v1
	v_mad_i64_i32 v[18:19], s[0:1], v18, s91, 0
	v_mad_i64_i32 v[20:21], s[0:1], v1, s91, 0
	v_or_b32_e32 v18, v18, v148
	v_mul_lo_u32 v183, v182, s11
	v_or_b32_e32 v20, v20, v148
	v_lshlrev_b64 v[18:19], 1, v[18:19]
	v_add_u32_e32 v26, v146, v183
	v_lshlrev_b64 v[20:21], 1, v[20:21]
	v_lshl_add_u64 v[22:23], s[92:93], 0, v[18:19]
	v_add_u32_e32 v27, v146, v184
	v_lshl_add_u64 v[18:19], s[40:41], 0, v[18:19]
	v_lshl_add_u64 v[24:25], s[92:93], 0, v[20:21]
	v_lshl_add_u64 v[20:21], s[40:41], 0, v[20:21]
	s_add_i32 s26, s26, s3
	v_lshrrev_b32_e32 v1, 2, v147
	v_lshlrev_b32_e32 v186, 2, v149
	v_and_b32_e32 v206, 63, v147
	v_and_or_b32 v1, v1, 3, v186
	s_or_b32 s3, s26, 31
	v_or_b32_e32 v185, s26, v205
	v_mul_u32_u24_e32 v187, 0x140, v1
	v_cmp_gt_u32_e64 s[36:37], 32, v206
	v_or_b32_e32 v190, 24, v186
	v_or_b32_e32 v191, 25, v186
	v_or_b32_e32 v192, 26, v186
	v_or_b32_e32 v193, 27, v186
	v_or_b32_e32 v194, 16, v186
	v_or_b32_e32 v195, 17, v186
	v_or_b32_e32 v196, 18, v186
	v_or_b32_e32 v197, 19, v186
	v_or_b32_e32 v198, 8, v186
	v_or_b32_e32 v199, 9, v186
	v_or_b32_e32 v200, 10, v186
	v_or_b32_e32 v201, 11, v186
	v_or_b32_e32 v202, 1, v186
	v_or_b32_e32 v203, 2, v186
	s_cmp_le_i32 s5, s3
	v_or_b32_e32 v204, 3, v186
	s_mov_b32 s86, 0xd9c7dd
	s_waitcnt vmcnt(3)
	ds_write_b128 v26, v[2:5]
	s_waitcnt vmcnt(2)
	ds_write_b128 v27, v[6:9] offset:34816
	s_waitcnt vmcnt(1)
	ds_write_b128 v26, v[10:13] offset:8704
	s_waitcnt vmcnt(0)
	ds_write_b128 v27, v[14:17] offset:45056
	s_waitcnt lgkmcnt(0)
	s_barrier
	global_load_dwordx4 v[128:131], v[22:23], off
	global_load_dwordx4 v[132:135], v[18:19], off
	global_load_dwordx4 v[136:139], v[24:25], off
	global_load_dwordx4 v[140:143], v[20:21], off
	v_lshlrev_b32_e32 v2, 1, v147
	v_lshlrev_b32_e32 v3, 3, v147
	v_and_b32_e32 v188, 32, v2
	v_and_b32_e32 v189, 24, v3
	s_cbranch_scc0 .LBB0_524
	v_add_u32_e32 v1, 0, v180
	s_or_b32 s21, s5, 32
	v_add3_u32 v207, 0, v187, v188
	s_cmp_gt_i32 s21, s3
	v_mad_u32_u24 v152, v205, s11, v1
	s_cbranch_scc1 .LBB0_525
	ds_read_b128 v[2:5], v152 offset:8704
	ds_read_b128 v[18:21], v152 offset:8736
	ds_read_b128 v[222:225], v152 offset:8768
	ds_read_b128 v[226:229], v152 offset:8800
	ds_read_b128 v[230:233], v152 offset:8832
	ds_read_b128 v[234:237], v152 offset:8864
	ds_read_b128 v[238:241], v152 offset:8896
	ds_read_b128 v[242:245], v152 offset:8928
	s_or_b32 s12, s5, 63
	s_mov_b64 s[0:1], -1
	s_cmp_lt_i32 s12, s26
	s_waitcnt lgkmcnt(7)
	v_mfma_f32_32x32x16_bf16 v[2:17], v[2:5], v[96:99], 0
	s_waitcnt lgkmcnt(6)
	v_mfma_f32_32x32x16_bf16 v[2:17], v[18:21], v[100:103], v[2:17]
	s_waitcnt lgkmcnt(5)
	v_mfma_f32_32x32x16_bf16 v[2:17], v[222:225], v[104:107], v[2:17]
	s_waitcnt lgkmcnt(4)
	v_mfma_f32_32x32x16_bf16 v[2:17], v[226:229], v[108:111], v[2:17]
	s_waitcnt lgkmcnt(3)
	v_mfma_f32_32x32x16_bf16 v[2:17], v[230:233], v[112:115], v[2:17]
	s_waitcnt lgkmcnt(2)
	v_mfma_f32_32x32x16_bf16 v[2:17], v[234:237], v[116:119], v[2:17]
	s_waitcnt lgkmcnt(1)
	v_mfma_f32_32x32x16_bf16 v[2:17], v[238:241], v[120:123], v[2:17]
	s_waitcnt lgkmcnt(0)
	v_mfma_f32_32x32x16_bf16 v[2:17], v[242:245], v[124:127], v[2:17]
	s_nop 11
	v_mul_f32_e32 v46, 0x3e0293ee, v3
	v_mul_f32_e32 v1, 0x3e0293ee, v5
	s_cbranch_scc1 .LBB0_519
	v_and_b32_e32 v18, 64, v217
	v_xor_b32_e32 v3, 32, v217
	v_add_u32_e32 v18, 64, v18
	v_cmp_lt_i32_e32 vcc, v3, v18
	v_mul_f32_e32 v18, 0x3e0293ee, v14
	v_exp_f32_e64 v19, -|v18|
	v_subrev_u32_e32 v5, s21, v185
	v_cndmask_b32_e32 v3, v217, v3, vcc
	v_cmp_lt_f32_e32 vcc, 0, v18
	v_add_f32_e32 v20, 1.0, v19
	v_rcp_f32_e32 v20, v20
	v_lshlrev_b32_e32 v3, 2, v3
	s_mov_b64 s[0:1], 0
	v_mul_f32_e32 v19, v19, v20
	v_cndmask_b32_e32 v18, v19, v20, vcc
	v_cndmask_b32_e32 v19, v20, v19, vcc
	v_cmp_lt_i32_e32 vcc, v190, v5
	s_nop 1
	v_cndmask_b32_e32 v20, 1.0, v19, vcc
	v_mul_f32_e32 v19, 0x3e0293ee, v15
	v_exp_f32_e64 v21, -|v19|
	v_cndmask_b32_e32 v18, 0, v18, vcc
	v_cmp_lt_f32_e32 vcc, 0, v19
	v_mov_b32_e32 v19, s27
	v_add_f32_e32 v22, 1.0, v21
	v_rcp_f32_e32 v22, v22
	s_nop 0
	v_mul_f32_e32 v21, v21, v22
	v_cndmask_b32_e32 v23, v21, v22, vcc
	v_cndmask_b32_e32 v21, v22, v21, vcc
	v_cmp_lt_i32_e32 vcc, v191, v5
	s_nop 1
	v_cndmask_b32_e32 v22, 1.0, v21, vcc
	v_mul_f32_e32 v21, v20, v22
	v_mul_f32_e32 v20, 0x3e0293ee, v16
	v_cndmask_b32_e32 v19, v19, v23, vcc
	v_exp_f32_e64 v23, -|v20|
	v_cmp_lt_f32_e32 vcc, 0, v20
	v_mov_b32_e32 v20, s27
	v_add_f32_e32 v24, 1.0, v23
	v_rcp_f32_e32 v24, v24
	s_nop 0
	v_mul_f32_e32 v23, v23, v24
	v_cndmask_b32_e32 v25, v23, v24, vcc
	v_cndmask_b32_e32 v23, v24, v23, vcc
	v_cmp_lt_i32_e32 vcc, v192, v5
	s_nop 1
	v_cndmask_b32_e32 v23, 1.0, v23, vcc
	v_mul_f32_e32 v24, v23, v21
	v_mul_f32_e32 v21, 0x3e0293ee, v17
	v_cndmask_b32_e32 v20, v20, v25, vcc
	v_exp_f32_e64 v25, -|v21|
	v_cmp_lt_f32_e32 vcc, 0, v21
	v_mov_b32_e32 v21, s27
	v_add_f32_e32 v26, 1.0, v25
	v_rcp_f32_e32 v26, v26
	s_nop 0
	v_mul_f32_e32 v25, v25, v26
	v_cndmask_b32_e32 v27, v25, v26, vcc
	v_cndmask_b32_e32 v25, v26, v25, vcc
	v_cmp_lt_i32_e32 vcc, v193, v5
	s_nop 1
	v_cndmask_b32_e32 v26, 1.0, v25, vcc
	v_cndmask_b32_e32 v21, v21, v27, vcc
	v_mul_f32_e32 v27, v26, v24
	v_mov_b32_e32 v24, v27
	v_mov_b32_e32 v28, v27
	s_nop 1
	v_permlane32_swap_b32_e32 v28, v24
	v_cndmask_b32_e64 v28, v28, v24, s[36:37]
	s_waitcnt lgkmcnt(0)
	v_cndmask_b32_e64 v25, 1.0, v28, s[36:37]
	v_mul_f32_e32 v24, v26, v25
	v_mul_f32_e32 v26, 0x3e0293ee, v10
	v_mul_f32_e32 v34, v27, v28
	v_exp_f32_e64 v27, -|v26|
	v_cmp_lt_f32_e32 vcc, 0, v26
	v_mov_b32_e32 v26, s27
	v_mul_f32_e32 v23, v23, v24
	v_add_f32_e32 v28, 1.0, v27
	v_rcp_f32_e32 v28, v28
	v_mul_f32_e32 v22, v22, v23
	v_pk_mul_f32 v[20:21], v[20:21], v[24:25]
	v_pk_mul_f32 v[18:19], v[18:19], v[22:23]
	v_mul_f32_e32 v27, v27, v28
	v_cndmask_b32_e32 v29, v27, v28, vcc
	v_cndmask_b32_e32 v27, v28, v27, vcc
	v_cmp_lt_i32_e32 vcc, v194, v5
	s_nop 1
	v_cndmask_b32_e32 v28, 1.0, v27, vcc
	v_mul_f32_e32 v27, 0x3e0293ee, v11
	v_cndmask_b32_e32 v26, v26, v29, vcc
	v_exp_f32_e64 v29, -|v27|
	v_cmp_lt_f32_e32 vcc, 0, v27
	v_mov_b32_e32 v27, s27
	v_add_f32_e32 v30, 1.0, v29
	v_rcp_f32_e32 v30, v30
	s_nop 0
	v_mul_f32_e32 v29, v29, v30
	v_cndmask_b32_e32 v31, v29, v30, vcc
	v_cndmask_b32_e32 v29, v30, v29, vcc
	v_cmp_lt_i32_e32 vcc, v195, v5
	s_nop 1
	v_cndmask_b32_e32 v30, 1.0, v29, vcc
	v_mul_f32_e32 v29, v28, v30
	v_mul_f32_e32 v28, 0x3e0293ee, v12
	v_cndmask_b32_e32 v27, v27, v31, vcc
	v_exp_f32_e64 v31, -|v28|
	v_cmp_lt_f32_e32 vcc, 0, v28
	v_mov_b32_e32 v28, s27
	v_add_f32_e32 v32, 1.0, v31
	v_rcp_f32_e32 v32, v32
	s_nop 0
	v_mul_f32_e32 v31, v31, v32
	v_cndmask_b32_e32 v33, v31, v32, vcc
	v_cndmask_b32_e32 v31, v32, v31, vcc
	v_cmp_lt_i32_e32 vcc, v196, v5
	s_nop 1
	v_cndmask_b32_e32 v31, 1.0, v31, vcc
	v_mul_f32_e32 v32, v31, v29
	v_mul_f32_e32 v29, 0x3e0293ee, v13
	v_cndmask_b32_e32 v28, v28, v33, vcc
	v_exp_f32_e64 v33, -|v29|
	v_cmp_lt_f32_e32 vcc, 0, v29
	v_mov_b32_e32 v29, s27
	v_add_f32_e32 v35, 1.0, v33
	v_rcp_f32_e32 v35, v35
	s_nop 0
	v_mul_f32_e32 v33, v33, v35
	v_cndmask_b32_e32 v36, v33, v35, vcc
	v_cndmask_b32_e32 v33, v35, v33, vcc
	v_cmp_lt_i32_e32 vcc, v197, v5
	s_nop 1
	v_cndmask_b32_e32 v35, 1.0, v33, vcc
	v_cndmask_b32_e32 v29, v29, v36, vcc
	v_mul_f32_e32 v36, v35, v32
	v_mov_b32_e32 v22, v36
	v_mov_b32_e32 v37, v36
	s_nop 1
	v_permlane32_swap_b32_e32 v37, v22
	v_cndmask_b32_e64 v37, v37, v22, s[36:37]
	s_waitcnt lgkmcnt(0)
	v_cndmask_b32_e64 v32, 1.0, v37, s[36:37]
	v_mul_f32_e32 v33, v34, v32
	v_mul_f32_e32 v32, v35, v33
	v_mul_f32_e32 v35, v36, v37
	v_mul_f32_e32 v42, v34, v35
	v_mul_f32_e32 v34, 0x3e0293ee, v6
	v_exp_f32_e64 v35, -|v34|
	v_cmp_lt_f32_e32 vcc, 0, v34
	v_mov_b32_e32 v34, s27
	v_mul_f32_e32 v31, v31, v32
	v_add_f32_e32 v36, 1.0, v35
	v_rcp_f32_e32 v36, v36
	v_mul_f32_e32 v30, v30, v31
	v_pk_mul_f32 v[28:29], v[28:29], v[32:33]
	v_pk_mul_f32 v[26:27], v[26:27], v[30:31]
	v_mul_f32_e32 v35, v35, v36
	v_cndmask_b32_e32 v37, v35, v36, vcc
	v_cndmask_b32_e32 v35, v36, v35, vcc
	v_cmp_lt_i32_e32 vcc, v198, v5
	s_nop 1
	v_cndmask_b32_e32 v36, 1.0, v35, vcc
	v_mul_f32_e32 v35, 0x3e0293ee, v7
	v_cndmask_b32_e32 v34, v34, v37, vcc
	v_exp_f32_e64 v37, -|v35|
	v_cmp_lt_f32_e32 vcc, 0, v35
	v_mov_b32_e32 v35, s27
	v_add_f32_e32 v38, 1.0, v37
	v_rcp_f32_e32 v38, v38
	s_nop 0
	v_mul_f32_e32 v37, v37, v38
	v_cndmask_b32_e32 v39, v37, v38, vcc
	v_cndmask_b32_e32 v37, v38, v37, vcc
	v_cmp_lt_i32_e32 vcc, v199, v5
	s_nop 1
	v_cndmask_b32_e32 v38, 1.0, v37, vcc
	v_mul_f32_e32 v37, v36, v38
	v_mul_f32_e32 v36, 0x3e0293ee, v8
	v_cndmask_b32_e32 v35, v35, v39, vcc
	v_exp_f32_e64 v39, -|v36|
	v_cmp_lt_f32_e32 vcc, 0, v36
	v_mov_b32_e32 v36, s27
	v_add_f32_e32 v40, 1.0, v39
	v_rcp_f32_e32 v40, v40
	s_nop 0
	v_mul_f32_e32 v39, v39, v40
	v_cndmask_b32_e32 v41, v39, v40, vcc
	v_cndmask_b32_e32 v39, v40, v39, vcc
	v_cmp_lt_i32_e32 vcc, v200, v5
	s_nop 1
	v_cndmask_b32_e32 v39, 1.0, v39, vcc
	v_mul_f32_e32 v40, v39, v37
	v_mul_f32_e32 v37, 0x3e0293ee, v9
	v_cndmask_b32_e32 v36, v36, v41, vcc
	v_exp_f32_e64 v41, -|v37|
	v_cmp_lt_f32_e32 vcc, 0, v37
	v_mov_b32_e32 v37, s27
	v_add_f32_e32 v43, 1.0, v41
	v_rcp_f32_e32 v43, v43
	s_nop 0
	v_mul_f32_e32 v41, v41, v43
	v_cndmask_b32_e32 v44, v41, v43, vcc
	v_cndmask_b32_e32 v41, v43, v41, vcc
	v_cmp_lt_i32_e32 vcc, v201, v5
	s_nop 1
	v_cndmask_b32_e32 v43, 1.0, v41, vcc
	v_cndmask_b32_e32 v37, v37, v44, vcc
	v_mul_f32_e32 v44, v43, v40
	v_mov_b32_e32 v22, v44
	v_mov_b32_e32 v45, v44
	s_nop 1
	v_permlane32_swap_b32_e32 v45, v22
	v_cndmask_b32_e64 v45, v45, v22, s[36:37]
	s_waitcnt lgkmcnt(0)
	v_cndmask_b32_e64 v40, 1.0, v45, s[36:37]
	v_mul_f32_e32 v41, v42, v40
	v_mul_f32_e32 v40, v43, v41
	v_mul_f32_e32 v43, v44, v45
	v_mul_f32_e32 v47, v43, v42
	v_mul_f32_e32 v42, 0x3e0293ee, v2
	v_exp_f32_e64 v43, -|v42|
	v_cmp_lt_f32_e32 vcc, 0, v42
	v_mov_b32_e32 v42, s27
	v_mul_f32_e32 v39, v39, v40
	v_add_f32_e32 v44, 1.0, v43
	v_rcp_f32_e32 v44, v44
	v_mul_f32_e32 v38, v38, v39
	v_pk_mul_f32 v[36:37], v[36:37], v[40:41]
	v_pk_mul_f32 v[34:35], v[34:35], v[38:39]
	v_mul_f32_e32 v43, v43, v44
	v_cndmask_b32_e32 v45, v43, v44, vcc
	v_cndmask_b32_e32 v43, v44, v43, vcc
	v_cmp_lt_i32_e32 vcc, v186, v5
	s_nop 1
	v_cndmask_b32_e32 v44, 1.0, v43, vcc
	v_exp_f32_e64 v43, -|v46|
	v_cndmask_b32_e32 v42, v42, v45, vcc
	v_cmp_lt_f32_e32 vcc, 0, v46
	v_add_f32_e32 v45, 1.0, v43
	v_rcp_f32_e32 v45, v45
	s_nop 0
	v_mul_f32_e32 v43, v43, v45
	v_cndmask_b32_e32 v48, v43, v45, vcc
	v_cndmask_b32_e32 v45, v45, v43, vcc
	v_cmp_lt_i32_e32 vcc, v202, v5
	v_mov_b32_e32 v43, s27
	s_nop 0
	v_cndmask_b32_e32 v50, 1.0, v45, vcc
	v_mul_f32_e32 v45, v44, v50
	v_mul_f32_e32 v44, 0x3e0293ee, v4
	v_cndmask_b32_e32 v43, v43, v48, vcc
	v_exp_f32_e64 v48, -|v44|
	v_cmp_lt_f32_e32 vcc, 0, v44
	v_mov_b32_e32 v44, s27
	v_add_f32_e32 v49, 1.0, v48
	v_rcp_f32_e32 v49, v49
	s_nop 0
	v_mul_f32_e32 v48, v48, v49
	v_cndmask_b32_e32 v51, v48, v49, vcc
	v_cndmask_b32_e32 v48, v49, v48, vcc
	v_cmp_lt_i32_e32 vcc, v203, v5
	s_nop 1
	v_cndmask_b32_e32 v44, v44, v51, vcc
	v_cndmask_b32_e32 v51, 1.0, v48, vcc
	v_mul_f32_e32 v48, v51, v45
	v_exp_f32_e64 v45, -|v1|
	v_cmp_lt_f32_e32 vcc, 0, v1
	v_add_f32_e32 v49, 1.0, v45
	v_rcp_f32_e32 v49, v49
	s_nop 0
	v_mul_f32_e32 v45, v45, v49
	v_cndmask_b32_e32 v52, v45, v49, vcc
	v_cndmask_b32_e32 v49, v49, v45, vcc
	v_cmp_lt_i32_e32 vcc, v204, v5
	v_mov_b32_e32 v5, s27
	s_nop 0
	v_cndmask_b32_e32 v45, v5, v52, vcc
	v_cndmask_b32_e32 v5, 1.0, v49, vcc
	v_mul_f32_e32 v52, v5, v48
	v_mov_b32_e32 v22, v52
	v_mov_b32_e32 v3, v52
	s_nop 1
	v_permlane32_swap_b32_e32 v3, v22
	v_cndmask_b32_e64 v3, v3, v22, s[36:37]
	s_waitcnt lgkmcnt(0)
	v_cndmask_b32_e64 v48, 1.0, v3, s[36:37]
	v_mul_f32_e32 v49, v47, v48
	v_mul_f32_e32 v48, v5, v49
	v_mul_f32_e32 v51, v51, v48
	v_mul_f32_e32 v50, v50, v51
	v_mul_f32_e32 v3, v52, v3
	v_pk_mul_f32 v[44:45], v[44:45], v[48:49]
	v_pk_mul_f32 v[42:43], v[42:43], v[50:51]
	v_mul_f32_e32 v153, v3, v47
.LBB0_519:
	s_andn2_b64 vcc, exec, s[0:1]
	s_cbranch_vccnz .LBB0_521
	v_mov_b32_e32 v18, v14
	v_mov_b32_e32 v19, v10
	v_pk_mul_f32 v[18:19], v[18:19], s[34:35] op_sel_hi:[1,0]
	v_and_b32_e32 v5, 64, v217
	v_exp_f32_e64 v20, -|v18|
	v_xor_b32_e32 v3, 32, v217
	v_add_u32_e32 v5, 64, v5
	v_exp_f32_e64 v21, -|v19|
	v_cmp_lt_i32_e32 vcc, v3, v5
	v_mov_b32_e32 v10, v15
	v_pk_mul_f32 v[10:11], v[10:11], s[34:35] op_sel_hi:[1,0]
	v_cndmask_b32_e32 v3, v217, v3, vcc
	v_lshlrev_b32_e32 v44, 2, v3
	v_add_f32_e32 v3, 1.0, v20
	v_rcp_f32_e32 v14, v3
	v_add_f32_e32 v3, 1.0, v21
	v_rcp_f32_e32 v15, v3
	v_exp_f32_e64 v22, -|v10|
	v_exp_f32_e64 v23, -|v11|
	v_cmp_lt_f32_e64 s[38:39], 0, v10
	v_pk_mul_f32 v[30:31], v[20:21], v[14:15]
	v_mov_b32_e32 v20, v16
	v_mov_b32_e32 v21, v12
	v_pk_mul_f32 v[20:21], v[20:21], s[34:35] op_sel_hi:[1,0]
	v_mov_b32_e32 v12, v17
	v_exp_f32_e64 v26, -|v20|
	v_exp_f32_e64 v27, -|v21|
	v_pk_mul_f32 v[12:13], v[12:13], s[34:35] op_sel_hi:[1,0]
	v_add_f32_e32 v3, 1.0, v22
	v_exp_f32_e64 v28, -|v12|
	v_exp_f32_e64 v29, -|v13|
	v_add_f32_e32 v10, 1.0, v26
	v_rcp_f32_e32 v24, v3
	v_add_f32_e32 v3, 1.0, v23
	v_rcp_f32_e32 v16, v10
	v_add_f32_e32 v10, 1.0, v27
	v_rcp_f32_e32 v25, v3
	v_rcp_f32_e32 v17, v10
	v_add_f32_e32 v10, 1.0, v28
	v_rcp_f32_e32 v32, v10
	v_add_f32_e32 v10, 1.0, v29
	v_rcp_f32_e32 v33, v10
	v_cmp_lt_f32_e64 s[0:1], 0, v18
	v_pk_mul_f32 v[22:23], v[22:23], v[24:25]
	v_cmp_lt_f32_e32 vcc, 0, v19
	v_cndmask_b32_e64 v3, v30, v14, s[0:1]
	v_cndmask_b32_e64 v18, v14, v30, s[0:1]
	v_cmp_lt_f32_e64 s[0:1], 0, v11
	v_cndmask_b32_e64 v5, v22, v24, s[38:39]
	v_pk_mul_f32 v[26:27], v[26:27], v[16:17]
	v_cmp_lt_f32_e64 s[44:45], 0, v20
	v_cndmask_b32_e32 v19, v15, v31, vcc
	v_cndmask_b32_e64 v11, v25, v23, s[0:1]
	v_cndmask_b32_e64 v10, v24, v22, s[38:39]
	v_cmp_lt_f32_e64 s[38:39], 0, v21
	v_cndmask_b32_e64 v20, v26, v16, s[44:45]
	v_pk_mul_f32 v[28:29], v[28:29], v[32:33]
	v_cmp_lt_f32_e64 s[46:47], 0, v12
	v_pk_mul_f32 v[18:19], v[18:19], v[10:11]
	v_cndmask_b32_e64 v35, v17, v27, s[38:39]
	v_cndmask_b32_e64 v34, v16, v26, s[44:45]
	v_cmp_lt_f32_e64 s[44:45], 0, v13
	v_pk_mul_f32 v[18:19], v[34:35], v[18:19]
	v_cndmask_b32_e64 v12, v32, v28, s[46:47]
	v_cndmask_b32_e64 v13, v33, v29, s[44:45]
	v_pk_mul_f32 v[36:37], v[12:13], v[18:19]
	v_mov_b32_e32 v14, v36
	v_mov_b32_e32 v38, v36
	s_nop 1
	v_permlane32_swap_b32_e32 v38, v14
	v_cndmask_b32_e64 v38, v38, v14, s[36:37]
	v_mov_b32_e32 v14, v37
	v_mov_b32_e32 v39, v37
	s_nop 1
	v_permlane32_swap_b32_e32 v39, v14
	v_cndmask_b32_e64 v39, v39, v14, s[36:37]
	v_cndmask_b32_e64 v40, v28, v32, s[46:47]
	v_pk_mul_f32 v[6:7], v[6:7], s[34:35] op_sel_hi:[1,0]
	v_cmp_lt_f32_e64 s[46:47], 0, v46
	s_waitcnt lgkmcnt(1)
	v_cndmask_b32_e64 v14, 1.0, v38, s[36:37]
	v_mul_f32_e32 v12, v12, v14
	v_mul_f32_e32 v20, v20, v12
	v_mul_f32_e32 v12, v34, v12
	v_mul_f32_e32 v19, v5, v12
	v_mul_f32_e32 v5, v10, v12
	v_mul_f32_e32 v18, v3, v5
	v_cndmask_b32_e64 v10, v27, v17, s[38:39]
	s_waitcnt lgkmcnt(0)
	v_cndmask_b32_e64 v5, 1.0, v39, s[36:37]
	v_pk_mul_f32 v[16:17], v[36:37], v[38:39]
	v_cndmask_b32_e64 v3, v29, v33, s[44:45]
	v_mul_f32_e32 v28, v16, v5
	v_mul_f32_e32 v29, v3, v28
	v_mov_b32_e32 v3, v8
	v_exp_f32_e64 v12, -|v46|
	v_pk_mul_f32 v[2:3], v[2:3], s[34:35] op_sel_hi:[1,0]
	v_mul_f32_e32 v21, v40, v14
	v_cndmask_b32_e64 v14, v23, v25, s[0:1]
	v_exp_f32_e64 v23, -|v3|
	v_add_f32_e32 v5, 1.0, v12
	v_rcp_f32_e32 v30, v5
	v_exp_f32_e64 v22, -|v2|
	v_add_f32_e32 v5, 1.0, v23
	v_rcp_f32_e32 v25, v5
	v_mov_b32_e32 v5, v9
	v_pk_mul_f32 v[4:5], v[4:5], s[34:35] op_sel_hi:[1,0]
	v_add_f32_e32 v24, 1.0, v22
	v_exp_f32_e64 v9, -|v5|
	v_exp_f32_e64 v8, -|v4|
	v_rcp_f32_e32 v24, v24
	v_exp_f32_e64 v27, -|v7|
	v_add_f32_e32 v26, 1.0, v9
	v_rcp_f32_e32 v33, v26
	v_add_f32_e32 v26, 1.0, v8
	v_rcp_f32_e32 v32, v26
	v_exp_f32_e64 v26, -|v6|
	v_pk_mul_f32 v[22:23], v[22:23], v[24:25]
	v_cmp_lt_f32_e64 s[0:1], 0, v3
	v_cmp_lt_f32_e64 s[48:49], 0, v7
	v_cmp_lt_f32_e64 s[50:51], 0, v6
	v_cndmask_b32_e64 v45, v23, v25, s[0:1]
	v_cndmask_b32_e64 v3, v25, v23, s[0:1]
	v_add_f32_e32 v23, 1.0, v26
	v_rcp_f32_e32 v36, v23
	v_add_f32_e32 v23, 1.0, v27
	v_rcp_f32_e32 v37, v23
	v_cmp_lt_f32_e64 s[0:1], 0, v2
	v_mul_f32_e32 v23, v12, v30
	v_pk_mul_f32 v[8:9], v[8:9], v[32:33]
	v_pk_mul_f32 v[26:27], v[26:27], v[36:37]
	v_cndmask_b32_e64 v2, v24, v22, s[0:1]
	v_cndmask_b32_e64 v12, v37, v27, s[48:49]
	v_cndmask_b32_e64 v25, v36, v26, s[50:51]
	v_cmp_lt_f32_e64 s[38:39], 0, v5
	v_cmp_lt_f32_e64 s[44:45], 0, v4
	v_cndmask_b32_e64 v38, v30, v23, s[46:47]
	v_mul_f32_e32 v39, v25, v12
	v_cndmask_b32_e64 v5, v33, v9, s[38:39]
	v_cndmask_b32_e64 v4, v32, v8, s[44:45]
	v_cndmask_b32_e64 v7, v27, v37, s[48:49]
	v_cndmask_b32_e64 v6, v26, v36, s[50:51]
	v_pk_mul_f32 v[26:27], v[2:3], v[38:39]
	v_exp_f32_e64 v42, -|v1|
	v_pk_mul_f32 v[40:41], v[4:5], v[26:27]
	v_mov_b32_e32 v2, v41
	v_mov_b32_e32 v43, v41
	s_nop 1
	v_permlane32_swap_b32_e32 v43, v2
	v_cndmask_b32_e64 v43, v43, v2, s[36:37]
	v_mul_f32_e32 v27, v13, v28
	v_add_f32_e32 v2, 1.0, v42
	v_rcp_f32_e32 v13, v2
	v_mov_b32_e32 v34, v16
	v_mov_b32_e32 v26, v17
	v_mul_f32_e32 v28, v10, v27
	s_waitcnt lgkmcnt(0)
	v_cndmask_b32_e64 v10, 1.0, v43, s[36:37]
	v_pk_mul_f32 v[16:17], v[34:35], v[26:27]
	v_cndmask_b32_e32 v15, v31, v15, vcc
	v_mul_f32_e32 v27, v14, v17
	v_cndmask_b32_e64 v14, v9, v33, s[38:39]
	v_pk_mul_f32 v[10:11], v[16:17], v[10:11]
	v_mov_b32_e32 v2, v5
	v_pk_mul_f32 v[14:15], v[14:15], v[10:11]
	v_pk_mul_f32 v[10:11], v[2:3], v[10:11]
	v_mov_b32_e32 v2, v3
	v_pk_mul_f32 v[2:3], v[2:3], v[10:11]
	v_mul_f32_e32 v5, v42, v13
	v_cmp_lt_f32_e32 vcc, 0, v1
	v_mul_f32_e32 v36, v45, v10
	v_pk_mul_f32 v[10:11], v[12:13], v[2:3]
	v_cndmask_b32_e32 v42, v13, v5, vcc
	v_mov_b32_e32 v11, v2
	v_pk_mul_f32 v[2:3], v[42:43], v[40:41]
	v_pk_mul_f32 v[34:35], v[6:7], v[10:11]
	v_mov_b32_e32 v44, v2
	v_mov_b32_e32 v6, v2
	s_nop 1
	v_permlane32_swap_b32_e32 v6, v44
	v_cndmask_b32_e64 v6, v6, v44, s[36:37]
	v_mov_b32_e32 v7, v16
	v_cndmask_b32_e32 v9, v5, v13, vcc
	v_cndmask_b32_e64 v10, v22, v24, s[0:1]
	v_cndmask_b32_e64 v11, v23, v30, s[46:47]
	s_waitcnt lgkmcnt(0)
	v_cndmask_b32_e64 v1, 1.0, v6, s[36:37]
	v_pk_mul_f32 v[2:3], v[2:3], v[6:7]
	v_cndmask_b32_e64 v8, v8, v32, s[44:45]
	v_mul_f32_e32 v7, v3, v1
	v_mul_f32_e32 v6, v42, v7
	v_mul_f32_e32 v5, v4, v6
	v_mul_f32_e32 v4, v38, v5
	v_pk_mul_f32 v[44:45], v[8:9], v[6:7]
	v_pk_mul_f32 v[42:43], v[10:11], v[4:5]
	v_mul_f32_e32 v153, v2, v3
	v_mov_b32_e32 v37, v14
	v_mov_b32_e32 v26, v15

.LBB0_526:
	ds_read_b128 v[2:5], v152
	ds_read_b128 v[6:9], v152 offset:32
	ds_read_b128 v[222:225], v152 offset:64
	ds_read_b128 v[226:229], v152 offset:96
	ds_read_b128 v[230:233], v152 offset:128
	ds_read_b128 v[234:237], v152 offset:160
	ds_read_b128 v[238:241], v152 offset:192
	ds_read_b128 v[242:245], v152 offset:224
	s_or_b32 s12, s5, 31
	s_mov_b64 s[0:1], -1
	s_cmp_lt_i32 s12, s26
	s_waitcnt lgkmcnt(7)
	v_mfma_f32_32x32x16_bf16 v[80:95], v[2:5], v[96:99], 0
	s_waitcnt lgkmcnt(6)
	v_mfma_f32_32x32x16_bf16 v[80:95], v[6:9], v[100:103], v[80:95]
	s_waitcnt lgkmcnt(5)
	v_mfma_f32_32x32x16_bf16 v[80:95], v[222:225], v[104:107], v[80:95]
	s_waitcnt lgkmcnt(4)
	v_mfma_f32_32x32x16_bf16 v[80:95], v[226:229], v[108:111], v[80:95]
	s_waitcnt lgkmcnt(3)
	v_mfma_f32_32x32x16_bf16 v[80:95], v[230:233], v[112:115], v[80:95]
	s_waitcnt lgkmcnt(2)
	v_mfma_f32_32x32x16_bf16 v[80:95], v[234:237], v[116:119], v[80:95]
	s_waitcnt lgkmcnt(1)
	v_mfma_f32_32x32x16_bf16 v[80:95], v[238:241], v[120:123], v[80:95]
	s_waitcnt lgkmcnt(0)
	v_mfma_f32_32x32x16_bf16 v[80:95], v[242:245], v[124:127], v[80:95]
	s_nop 11
	v_mul_f32_e32 v209, 0x3e0293ee, v89
	v_mul_f32_e32 v152, 0x3e0293ee, v91
	v_mul_f32_e32 v208, 0x3e0293ee, v81
	v_mul_f32_e32 v1, 0x3e0293ee, v83
	s_cbranch_scc1 .LBB0_528
	v_and_b32_e32 v3, 64, v217
	v_xor_b32_e32 v2, 32, v217
	v_add_u32_e32 v3, 64, v3
	v_cmp_lt_i32_e32 vcc, v2, v3
	v_subrev_u32_e32 v83, s5, v185
	s_mov_b64 s[0:1], 0
	v_cndmask_b32_e32 v2, v217, v2, vcc
	v_lshlrev_b32_e32 v81, 2, v2
	v_mul_f32_e32 v2, 0x3e0293ee, v92
	v_exp_f32_e64 v3, -|v2|
	v_cmp_lt_f32_e32 vcc, 0, v2
	v_add_f32_e32 v4, 1.0, v3
	v_rcp_f32_e32 v4, v4
	s_nop 0
	v_mul_f32_e32 v3, v3, v4
	v_cndmask_b32_e32 v2, v3, v4, vcc
	v_cndmask_b32_e32 v3, v4, v3, vcc
	v_cmp_lt_i32_e32 vcc, v190, v83
	s_nop 1
	v_cndmask_b32_e32 v4, 1.0, v3, vcc
	v_mul_f32_e32 v3, 0x3e0293ee, v93
	v_exp_f32_e64 v5, -|v3|
	v_cndmask_b32_e32 v2, 0, v2, vcc
	v_cmp_lt_f32_e32 vcc, 0, v3
	v_mov_b32_e32 v3, s27
	v_add_f32_e32 v6, 1.0, v5
	v_rcp_f32_e32 v6, v6
	s_nop 0
	v_mul_f32_e32 v5, v5, v6
	v_cndmask_b32_e32 v7, v5, v6, vcc
	v_cndmask_b32_e32 v5, v6, v5, vcc
	v_cmp_lt_i32_e32 vcc, v191, v83
	s_nop 1
	v_cndmask_b32_e32 v6, 1.0, v5, vcc
	v_mul_f32_e32 v5, v4, v6
	v_mul_f32_e32 v4, 0x3e0293ee, v94
	v_cndmask_b32_e32 v3, v3, v7, vcc
	v_exp_f32_e64 v7, -|v4|
	v_cmp_lt_f32_e32 vcc, 0, v4
	v_mov_b32_e32 v4, s27
	v_add_f32_e32 v8, 1.0, v7
	v_rcp_f32_e32 v8, v8
	s_nop 0
	v_mul_f32_e32 v7, v7, v8
	v_cndmask_b32_e32 v9, v7, v8, vcc
	v_cndmask_b32_e32 v7, v8, v7, vcc
	v_cmp_lt_i32_e32 vcc, v192, v83
	s_nop 1
	v_cndmask_b32_e32 v7, 1.0, v7, vcc
	v_mul_f32_e32 v8, v7, v5
	v_mul_f32_e32 v5, 0x3e0293ee, v95
	v_cndmask_b32_e32 v4, v4, v9, vcc
	v_exp_f32_e64 v9, -|v5|
	v_cmp_lt_f32_e32 vcc, 0, v5
	v_mov_b32_e32 v5, s27
	v_add_f32_e32 v10, 1.0, v9
	v_rcp_f32_e32 v10, v10
	s_nop 0
	v_mul_f32_e32 v9, v9, v10
	v_cndmask_b32_e32 v11, v9, v10, vcc
	v_cndmask_b32_e32 v9, v10, v9, vcc
	v_cmp_lt_i32_e32 vcc, v193, v83
	s_nop 1
	v_cndmask_b32_e32 v10, 1.0, v9, vcc
	v_cndmask_b32_e32 v5, v5, v11, vcc
	v_mul_f32_e32 v11, v10, v8
	v_mov_b32_e32 v8, v11
	v_mov_b32_e32 v12, v11
	s_nop 1
	v_permlane32_swap_b32_e32 v12, v8
	v_cndmask_b32_e64 v12, v12, v8, s[36:37]
	s_waitcnt lgkmcnt(0)
	v_cndmask_b32_e64 v8, 1.0, v12, s[36:37]
	v_mul_f32_e32 v9, v153, v8
	v_mul_f32_e32 v8, v10, v9
	v_mul_f32_e32 v10, v11, v12
	v_mul_f32_e32 v89, v153, v10
	v_mul_f32_e32 v10, 0x3e0293ee, v88
	v_exp_f32_e64 v11, -|v10|
	v_cmp_lt_f32_e32 vcc, 0, v10
	v_mov_b32_e32 v10, s27
	v_mul_f32_e32 v7, v7, v8
	v_add_f32_e32 v12, 1.0, v11
	v_rcp_f32_e32 v12, v12
	v_mul_f32_e32 v6, v6, v7
	v_pk_mul_f32 v[2:3], v[2:3], v[6:7]
	v_pk_mul_f32 v[4:5], v[4:5], v[8:9]
	v_mul_f32_e32 v11, v11, v12
	v_cndmask_b32_e32 v13, v11, v12, vcc
	v_cndmask_b32_e32 v11, v12, v11, vcc
	v_cmp_lt_i32_e32 vcc, v194, v83
	s_nop 1
	v_cndmask_b32_e32 v12, 1.0, v11, vcc
	v_exp_f32_e64 v11, -|v209|
	v_cndmask_b32_e32 v10, v10, v13, vcc
	v_cmp_lt_f32_e32 vcc, 0, v209
	v_add_f32_e32 v13, 1.0, v11
	v_rcp_f32_e32 v13, v13
	s_nop 0
	v_mul_f32_e32 v11, v11, v13
	v_cndmask_b32_e32 v14, v11, v13, vcc
	v_cndmask_b32_e32 v13, v13, v11, vcc
	v_cmp_lt_i32_e32 vcc, v195, v83
	v_mov_b32_e32 v11, s27
	s_nop 0
	v_cndmask_b32_e32 v11, v11, v14, vcc
	v_cndmask_b32_e32 v14, 1.0, v13, vcc
	v_mul_f32_e32 v13, v12, v14
	v_mul_f32_e32 v12, 0x3e0293ee, v90
	v_exp_f32_e64 v15, -|v12|
	v_cmp_lt_f32_e32 vcc, 0, v12
	v_mov_b32_e32 v12, s27
	v_add_f32_e32 v91, 1.0, v15
	v_rcp_f32_e32 v91, v91
	s_nop 0
	v_mul_f32_e32 v15, v15, v91
	v_cndmask_b32_e32 v154, v15, v91, vcc
	v_cndmask_b32_e32 v15, v91, v15, vcc
	v_cmp_lt_i32_e32 vcc, v196, v83
	s_nop 1
	v_cndmask_b32_e32 v15, 1.0, v15, vcc
	v_mul_f32_e32 v91, v15, v13
	v_exp_f32_e64 v13, -|v152|
	v_cndmask_b32_e32 v12, v12, v154, vcc
	v_cmp_lt_f32_e32 vcc, 0, v152
	v_add_f32_e32 v154, 1.0, v13
	v_rcp_f32_e32 v154, v154
	s_nop 0
	v_mul_f32_e32 v13, v13, v154
	v_cndmask_b32_e32 v155, v13, v154, vcc
	v_cndmask_b32_e32 v154, v154, v13, vcc
	v_cmp_lt_i32_e32 vcc, v197, v83
	v_mov_b32_e32 v13, s27
	s_nop 0
	v_cndmask_b32_e32 v154, 1.0, v154, vcc
	v_mul_f32_e32 v91, v154, v91
	v_mov_b32_e32 v6, v91
	v_mov_b32_e32 v156, v91
	s_nop 1
	v_permlane32_swap_b32_e32 v156, v6
	v_cndmask_b32_e64 v156, v156, v6, s[36:37]
	v_cndmask_b32_e32 v13, v13, v155, vcc
	s_waitcnt lgkmcnt(0)
	v_cndmask_b32_e64 v155, 1.0, v156, s[36:37]
	v_mul_f32_e32 v91, v91, v156
	v_mul_f32_e32 v155, v89, v155
	v_mul_f32_e32 v91, v91, v89
	v_mul_f32_e32 v89, 0x3e0293ee, v84
	v_exp_f32_e64 v156, -|v89|
	v_cmp_lt_f32_e32 vcc, 0, v89
	v_mul_f32_e32 v154, v154, v155
	v_mul_f32_e32 v15, v15, v154
	v_add_f32_e32 v157, 1.0, v156
	v_rcp_f32_e32 v157, v157
	v_mul_f32_e32 v14, v14, v15
	v_pk_mul_f32 v[12:13], v[12:13], v[154:155]
	v_pk_mul_f32 v[10:11], v[10:11], v[14:15]
	v_mul_f32_e32 v156, v156, v157
	v_cndmask_b32_e32 v89, v156, v157, vcc
	v_cndmask_b32_e32 v157, v157, v156, vcc
	v_cmp_lt_i32_e32 vcc, v198, v83
	v_mov_b32_e32 v156, s27
	s_nop 0
	v_cndmask_b32_e32 v156, v156, v89, vcc
	v_mul_f32_e32 v89, 0x3e0293ee, v85
	v_cndmask_b32_e32 v158, 1.0, v157, vcc
	v_exp_f32_e64 v157, -|v89|
	v_cmp_lt_f32_e32 vcc, 0, v89
	v_mov_b32_e32 v89, s27
	v_add_f32_e32 v159, 1.0, v157
	v_rcp_f32_e32 v159, v159
	s_nop 0
	v_mul_f32_e32 v157, v157, v159
	v_cndmask_b32_e32 v160, v157, v159, vcc
	v_cndmask_b32_e32 v159, v159, v157, vcc
	v_cmp_lt_i32_e32 vcc, v199, v83
	s_nop 1
	v_cndmask_b32_e32 v157, v89, v160, vcc
	v_cndmask_b32_e32 v160, 1.0, v159, vcc
	v_mul_f32_e32 v89, v158, v160
	v_mul_f32_e32 v158, 0x3e0293ee, v86
	v_exp_f32_e64 v159, -|v158|
	v_cmp_lt_f32_e32 vcc, 0, v158
	v_mov_b32_e32 v158, s27
	v_add_f32_e32 v161, 1.0, v159
	v_rcp_f32_e32 v161, v161
	s_nop 0
	v_mul_f32_e32 v159, v159, v161
	v_cndmask_b32_e32 v162, v159, v161, vcc
	v_cndmask_b32_e32 v159, v161, v159, vcc
	v_cmp_lt_i32_e32 vcc, v200, v83
	s_nop 1
	v_cndmask_b32_e32 v161, 1.0, v159, vcc
	v_cndmask_b32_e32 v158, v158, v162, vcc
	v_mul_f32_e32 v162, v161, v89
	v_mul_f32_e32 v89, 0x3e0293ee, v87
	v_exp_f32_e64 v159, -|v89|
	v_cmp_lt_f32_e32 vcc, 0, v89
	v_mov_b32_e32 v89, s27
	v_add_f32_e32 v163, 1.0, v159
	v_rcp_f32_e32 v163, v163
	s_nop 0
	v_mul_f32_e32 v159, v159, v163
	v_cndmask_b32_e32 v164, v159, v163, vcc
	v_cndmask_b32_e32 v163, v163, v159, vcc
	v_cmp_lt_i32_e32 vcc, v201, v83
	s_nop 1
	v_cndmask_b32_e32 v159, v89, v164, vcc
	v_cndmask_b32_e32 v89, 1.0, v163, vcc
	v_mul_f32_e32 v164, v89, v162
	v_mov_b32_e32 v6, v164
	v_mov_b32_e32 v165, v164
	s_nop 1
	v_permlane32_swap_b32_e32 v165, v6
	v_cndmask_b32_e64 v165, v165, v6, s[36:37]
	s_waitcnt lgkmcnt(0)
	v_cndmask_b32_e64 v162, 1.0, v165, s[36:37]
	v_mul_f32_e32 v163, v91, v162
	v_mul_f32_e32 v162, v89, v163
	v_mul_f32_e32 v89, v164, v165
	v_mul_f32_e32 v91, v89, v91
	v_mul_f32_e32 v89, 0x3e0293ee, v80
	v_exp_f32_e64 v164, -|v89|
	v_cmp_lt_f32_e32 vcc, 0, v89
	v_mul_f32_e32 v161, v161, v162
	v_mul_f32_e32 v160, v160, v161
	v_add_f32_e32 v165, 1.0, v164
	v_rcp_f32_e32 v165, v165
	v_pk_mul_f32 v[158:159], v[158:159], v[162:163]
	v_pk_mul_f32 v[156:157], v[156:157], v[160:161]
	v_mul_f32_e32 v164, v164, v165
	v_cndmask_b32_e32 v89, v164, v165, vcc
	v_cndmask_b32_e32 v165, v165, v164, vcc
	v_cmp_lt_i32_e32 vcc, v186, v83
	v_mov_b32_e32 v164, s27
	s_nop 0
	v_cndmask_b32_e32 v164, v164, v89, vcc
	v_exp_f32_e64 v89, -|v208|
	v_cndmask_b32_e32 v178, 1.0, v165, vcc
	v_cmp_lt_f32_e32 vcc, 0, v208
	v_add_f32_e32 v165, 1.0, v89
	v_rcp_f32_e32 v165, v165
	s_nop 0
	v_mul_f32_e32 v89, v89, v165
	v_cndmask_b32_e32 v179, v89, v165, vcc
	v_cndmask_b32_e32 v222, v165, v89, vcc
	v_cmp_lt_i32_e32 vcc, v202, v83
	v_mov_b32_e32 v89, s27
	s_nop 0
	v_cndmask_b32_e32 v165, v89, v179, vcc
	v_cndmask_b32_e32 v89, 1.0, v222, vcc
	v_mul_f32_e32 v179, v178, v89
	v_mul_f32_e32 v178, 0x3e0293ee, v82
	v_exp_f32_e64 v222, -|v178|
	v_cmp_lt_f32_e32 vcc, 0, v178
	v_mov_b32_e32 v178, s27
	v_add_f32_e32 v223, 1.0, v222
	v_rcp_f32_e32 v223, v223
	s_nop 0
	v_mul_f32_e32 v222, v222, v223
	v_cndmask_b32_e32 v224, v222, v223, vcc
	v_cndmask_b32_e32 v222, v223, v222, vcc
	v_cmp_lt_i32_e32 vcc, v203, v83
	s_nop 1
	v_cndmask_b32_e32 v178, v178, v224, vcc
	v_cndmask_b32_e32 v224, 1.0, v222, vcc
	v_mul_f32_e32 v222, v224, v179
	v_exp_f32_e64 v179, -|v1|
	v_cmp_lt_f32_e32 vcc, 0, v1
	v_add_f32_e32 v223, 1.0, v179
	v_rcp_f32_e32 v223, v223
	s_nop 0
	v_mul_f32_e32 v179, v179, v223
	v_cndmask_b32_e32 v225, v179, v223, vcc
	v_cndmask_b32_e32 v223, v223, v179, vcc
	v_cmp_lt_i32_e32 vcc, v204, v83
	v_mov_b32_e32 v83, s27
	s_nop 0
	v_cndmask_b32_e32 v179, v83, v225, vcc
	v_cndmask_b32_e32 v83, 1.0, v223, vcc
	v_mul_f32_e32 v226, v83, v222
	v_mov_b32_e32 v6, v226
	v_mov_b32_e32 v81, v226
	s_nop 1
	v_permlane32_swap_b32_e32 v81, v6
	v_cndmask_b32_e64 v81, v81, v6, s[36:37]
	s_waitcnt lgkmcnt(0)
	v_cndmask_b32_e64 v222, 1.0, v81, s[36:37]
	v_mul_f32_e32 v223, v91, v222
	v_mul_f32_e32 v222, v83, v223
	v_mul_f32_e32 v225, v224, v222
	v_mul_f32_e32 v224, v89, v225
	v_mul_f32_e32 v6, v226, v81
	v_pk_mul_f32 v[178:179], v[178:179], v[222:223]
	v_pk_mul_f32 v[164:165], v[164:165], v[224:225]
	v_mul_f32_e32 v6, v6, v91
.LBB0_528:
	s_andn2_b64 vcc, exec, s[0:1]
	s_cbranch_vccnz .LBB0_530
	v_and_b32_e32 v3, 64, v217
	v_xor_b32_e32 v2, 32, v217
	v_add_u32_e32 v3, 64, v3
	v_exp_f32_e64 v81, -|v209|
	v_cmp_lt_i32_e32 vcc, v2, v3
	v_mov_b32_e32 v89, v94
	v_mov_b32_e32 v91, v95
	v_cndmask_b32_e32 v2, v217, v2, vcc
	v_lshlrev_b32_e32 v160, 2, v2
	v_pk_mul_f32 v[2:3], v[88:89], s[34:35] op_sel_hi:[1,0]
	v_add_f32_e32 v4, 1.0, v81
	v_exp_f32_e64 v5, -|v3|
	v_rcp_f32_e32 v83, v4
	v_exp_f32_e64 v4, -|v2|
	v_pk_mul_f32 v[8:9], v[90:91], s[34:35] op_sel_hi:[1,0]
	v_add_f32_e32 v6, 1.0, v5
	v_rcp_f32_e32 v7, v6
	v_add_f32_e32 v6, 1.0, v4
	v_rcp_f32_e32 v6, v6
	v_exp_f32_e64 v11, -|v9|
	v_exp_f32_e64 v10, -|v8|
	v_cmp_lt_f32_e32 vcc, 0, v3
	v_pk_mul_f32 v[14:15], v[4:5], v[6:7]
	v_pk_mul_f32 v[4:5], v[92:93], s[34:35] op_sel_hi:[1,0]
	v_add_f32_e32 v12, 1.0, v11
	v_exp_f32_e64 v88, -|v4|
	v_exp_f32_e64 v89, -|v5|
	v_cndmask_b32_e32 v155, v15, v7, vcc
	v_cndmask_b32_e32 v3, v7, v15, vcc
	v_add_f32_e32 v7, 1.0, v88
	v_rcp_f32_e32 v13, v12
	v_add_f32_e32 v12, 1.0, v10
	v_rcp_f32_e32 v90, v7
	v_add_f32_e32 v7, 1.0, v89
	v_rcp_f32_e32 v12, v12
	v_rcp_f32_e32 v91, v7
	v_cmp_lt_f32_e64 s[0:1], 0, v9
	v_cmp_lt_f32_e64 s[44:45], 0, v5
	v_pk_mul_f32 v[10:11], v[10:11], v[12:13]
	v_pk_mul_f32 v[88:89], v[88:89], v[90:91]
	v_cmp_lt_f32_e64 s[46:47], 0, v4
	v_cndmask_b32_e64 v156, v11, v13, s[0:1]
	v_cmp_lt_f32_e32 vcc, 0, v2
	v_cndmask_b32_e64 v9, v13, v11, s[0:1]
	v_mul_f32_e32 v7, v81, v83
	v_cmp_lt_f32_e64 s[38:39], 0, v209
	v_cndmask_b32_e64 v11, v91, v89, s[44:45]
	v_cndmask_b32_e64 v4, v90, v88, s[46:47]
	v_cndmask_b32_e32 v2, v6, v14, vcc
	v_cmp_lt_f32_e64 s[0:1], 0, v8
	v_cndmask_b32_e64 v92, v83, v7, s[38:39]
	v_mul_f32_e32 v93, v4, v11
	v_exp_f32_e64 v154, -|v152|
	v_cndmask_b32_e64 v8, v12, v10, s[0:1]
	v_pk_mul_f32 v[4:5], v[2:3], v[92:93]
	v_cndmask_b32_e64 v95, v89, v91, s[44:45]
	v_cndmask_b32_e64 v94, v88, v90, s[46:47]
	v_pk_mul_f32 v[88:89], v[8:9], v[4:5]
	v_mov_b32_e32 v2, v89
	v_mov_b32_e32 v91, v89
	s_nop 1
	v_permlane32_swap_b32_e32 v91, v2
	v_cndmask_b32_e64 v91, v91, v2, s[36:37]
	v_add_f32_e32 v2, 1.0, v154
	v_rcp_f32_e32 v13, v2
	v_cmp_lt_f32_e64 s[44:45], 0, v152
	v_cndmask_b32_e32 v6, v14, v6, vcc
	s_waitcnt lgkmcnt(0)
	v_cndmask_b32_e64 v2, 1.0, v91, s[36:37]
	v_mul_f32_e32 v2, v153, v2
	v_mul_f32_e32 v5, v156, v2
	v_mul_f32_e32 v2, v9, v2
	v_mul_f32_e32 v9, v154, v13
	v_cndmask_b32_e64 v90, v13, v9, s[44:45]
	v_pk_mul_f32 v[88:89], v[90:91], v[88:89]
	v_mov_b32_e32 v4, v88
	v_mov_b32_e32 v152, v88
	s_nop 1
	v_permlane32_swap_b32_e32 v152, v4
	v_cndmask_b32_e64 v152, v152, v4, s[36:37]
	v_mul_f32_e32 v3, v3, v2
	v_mul_f32_e32 v4, v155, v2
	v_mul_f32_e32 v2, v11, v3
	v_cndmask_b32_e64 v11, v9, v13, s[44:45]
	s_waitcnt lgkmcnt(0)
	v_cndmask_b32_e64 v9, 1.0, v152, s[36:37]
	v_pk_mul_f32 v[14:15], v[88:89], v[152:153]
	v_cndmask_b32_e64 v10, v10, v12, s[0:1]
	v_mul_f32_e32 v89, v15, v9
	v_mul_f32_e32 v88, v90, v89
	v_mov_b32_e32 v81, v86
	v_exp_f32_e64 v152, -|v208|
	v_pk_mul_f32 v[12:13], v[10:11], v[88:89]
	v_pk_mul_f32 v[10:11], v[80:81], s[34:35] op_sel_hi:[1,0]
	v_cndmask_b32_e64 v7, v7, v83, s[38:39]
	v_exp_f32_e64 v81, -|v11|
	v_exp_f32_e64 v80, -|v10|
	v_add_f32_e32 v83, 1.0, v152
	v_mul_f32_e32 v9, v8, v88
	v_rcp_f32_e32 v161, v83
	v_add_f32_e32 v83, 1.0, v81
	v_add_f32_e32 v88, 1.0, v80
	v_rcp_f32_e32 v89, v83
	v_rcp_f32_e32 v88, v88
	v_mov_b32_e32 v83, v87
	v_cmp_lt_f32_e32 vcc, 0, v11
	v_pk_mul_f32 v[82:83], v[82:83], s[34:35] op_sel_hi:[1,0]
	v_pk_mul_f32 v[80:81], v[80:81], v[88:89]
	v_exp_f32_e64 v87, -|v83|
	v_cndmask_b32_e32 v156, v81, v89, vcc
	v_cndmask_b32_e32 v93, v89, v81, vcc
	v_cmp_lt_f32_e32 vcc, 0, v10
	v_pk_mul_f32 v[10:11], v[84:85], s[34:35] op_sel_hi:[1,0]
	v_exp_f32_e64 v86, -|v82|
	v_exp_f32_e64 v84, -|v10|
	v_exp_f32_e64 v85, -|v11|
	v_add_f32_e32 v90, 1.0, v87
	v_pk_mul_f32 v[2:3], v[94:95], v[2:3]
	v_add_f32_e32 v81, 1.0, v84
	v_rcp_f32_e32 v91, v90
	v_add_f32_e32 v90, 1.0, v86
	v_rcp_f32_e32 v94, v81
	v_add_f32_e32 v81, 1.0, v85
	v_rcp_f32_e32 v90, v90
	v_rcp_f32_e32 v95, v81
	v_cmp_lt_f32_e64 s[0:1], 0, v83
	v_cmp_lt_f32_e64 s[44:45], 0, v11
	v_pk_mul_f32 v[86:87], v[86:87], v[90:91]
	v_pk_mul_f32 v[84:85], v[84:85], v[94:95]
	v_cmp_lt_f32_e64 s[46:47], 0, v10
	v_cndmask_b32_e64 v157, v87, v91, s[0:1]
	v_cndmask_b32_e64 v83, v91, v87, s[0:1]
	v_mul_f32_e32 v81, v152, v161
	v_cmp_lt_f32_e64 s[38:39], 0, v208
	v_cndmask_b32_e64 v87, v95, v85, s[44:45]
	v_cndmask_b32_e64 v10, v94, v84, s[46:47]
	v_mul_f32_e32 v8, v92, v9
	v_cndmask_b32_e32 v92, v88, v80, vcc
	v_cmp_lt_f32_e64 s[0:1], 0, v82
	v_cndmask_b32_e64 v152, v161, v81, s[38:39]
	v_mul_f32_e32 v153, v10, v87
	v_cndmask_b32_e64 v82, v90, v86, s[0:1]
	v_pk_mul_f32 v[10:11], v[92:93], v[152:153]
	v_exp_f32_e64 v162, -|v1|
	v_cndmask_b32_e64 v155, v85, v95, s[44:45]
	v_cndmask_b32_e64 v154, v84, v94, s[46:47]
	v_pk_mul_f32 v[84:85], v[82:83], v[10:11]
	v_mov_b32_e32 v10, v85
	v_mov_b32_e32 v95, v85
	s_nop 1
	v_permlane32_swap_b32_e32 v95, v10
	v_cndmask_b32_e64 v95, v95, v10, s[36:37]
	v_pk_mul_f32 v[10:11], v[6:7], v[8:9]
	v_pk_mul_f32 v[6:7], v[14:15], v[14:15] op_sel:[0,1] op_sel_hi:[1,0]
	v_cmp_lt_f32_e64 s[44:45], 0, v1
	v_add_f32_e32 v7, 1.0, v162
	v_rcp_f32_e32 v7, v7
	s_waitcnt lgkmcnt(0)
	v_cndmask_b32_e64 v8, 1.0, v95, s[36:37]
	v_mul_f32_e32 v8, v6, v8
	v_mul_f32_e32 v159, v157, v8
	v_mul_f32_e32 v8, v83, v8
	v_mul_f32_e32 v9, v93, v8
	v_mul_f32_e32 v15, v162, v7
	v_mul_f32_e32 v158, v156, v8
	v_mul_f32_e32 v8, v87, v9
	v_cndmask_b32_e64 v94, v7, v15, s[44:45]
	v_pk_mul_f32 v[156:157], v[154:155], v[8:9]
	v_pk_mul_f32 v[8:9], v[94:95], v[84:85]
	v_mov_b32_e32 v160, v8
	v_mov_b32_e32 v14, v8
	s_nop 1
	v_permlane32_swap_b32_e32 v14, v160
	v_cndmask_b32_e64 v14, v14, v160, s[36:37]
	v_cndmask_b32_e64 v85, v15, v7, s[44:45]
	v_mov_b32_e32 v15, v6
	v_cndmask_b32_e64 v84, v86, v90, s[0:1]
	v_cndmask_b32_e32 v80, v80, v88, vcc
	s_waitcnt lgkmcnt(0)
	v_cndmask_b32_e64 v1, 1.0, v14, s[36:37]
	v_pk_mul_f32 v[6:7], v[8:9], v[14:15]
	v_cndmask_b32_e64 v81, v81, v161, s[38:39]
	v_mul_f32_e32 v9, v7, v1
	v_mul_f32_e32 v8, v94, v9
	v_pk_mul_f32 v[178:179], v[84:85], v[8:9]
	v_mul_f32_e32 v9, v82, v8
	v_mul_f32_e32 v8, v152, v9
	v_pk_mul_f32 v[164:165], v[80:81], v[8:9]
	v_mul_f32_e32 v6, v6, v7

.LBB0_539:
	s_cmp_gt_i32 s84, s3
	s_cselect_b64 s[0:1], -1, 0
	s_or_b64 s[0:1], s[50:51], s[0:1]
	s_and_b64 vcc, exec, s[0:1]
	s_cbranch_vccnz .LBB0_553
	v_add3_u32 v205, s28, v187, v188
	s_or_b32 s28, s84, 32
	s_cmp_gt_i32 s28, s3
	v_add_u32_e32 v206, s21, v180
	s_cbranch_scc1 .LBB0_547
	v_cmp_gt_f32_e32 vcc, s86, v153
	s_cmp_eq_u64 vcc, -1
	s_cbranch_scc1 .LBB0_547
	v_add_u32_e32 v10, v206, v1
	ds_read_b128 v[2:5], v10 offset:8704
	ds_read_b128 v[6:9], v10 offset:8736
	ds_read_b128 v[222:225], v10 offset:8768
	ds_read_b128 v[226:229], v10 offset:8800
	ds_read_b128 v[230:233], v10 offset:8832
	ds_read_b128 v[234:237], v10 offset:8864
	ds_read_b128 v[238:241], v10 offset:8896
	ds_read_b128 v[242:245], v10 offset:8928
	s_or_b32 s12, s84, 63
	s_mov_b64 s[0:1], -1
	s_cmp_lt_i32 s12, s26
	s_waitcnt lgkmcnt(7)
	v_mfma_f32_32x32x16_bf16 v[80:95], v[2:5], v[96:99], 0
	s_waitcnt lgkmcnt(6)
	v_mfma_f32_32x32x16_bf16 v[80:95], v[6:9], v[100:103], v[80:95]
	s_waitcnt lgkmcnt(5)
	v_mfma_f32_32x32x16_bf16 v[80:95], v[222:225], v[104:107], v[80:95]
	s_waitcnt lgkmcnt(4)
	v_mfma_f32_32x32x16_bf16 v[80:95], v[226:229], v[108:111], v[80:95]
	s_waitcnt lgkmcnt(3)
	v_mfma_f32_32x32x16_bf16 v[80:95], v[230:233], v[112:115], v[80:95]
	s_waitcnt lgkmcnt(2)
	v_mfma_f32_32x32x16_bf16 v[80:95], v[234:237], v[116:119], v[80:95]
	s_waitcnt lgkmcnt(1)
	v_mfma_f32_32x32x16_bf16 v[80:95], v[238:241], v[120:123], v[80:95]
	s_waitcnt lgkmcnt(0)
	v_mfma_f32_32x32x16_bf16 v[80:95], v[242:245], v[124:127], v[80:95]
	s_nop 11
	v_mul_f32_e32 v209, 0x3e0293ee, v89
	v_mul_f32_e32 v152, 0x3e0293ee, v91
	v_mul_f32_e32 v208, 0x3e0293ee, v81
	v_mul_f32_e32 v207, 0x3e0293ee, v83
	s_cbranch_scc1 .LBB0_544
	v_and_b32_e32 v3, 64, v217
	v_xor_b32_e32 v2, 32, v217
	v_add_u32_e32 v3, 64, v3
	v_cmp_lt_i32_e32 vcc, v2, v3
	v_subrev_u32_e32 v83, s28, v185
	s_mov_b64 s[0:1], 0
	v_cndmask_b32_e32 v2, v217, v2, vcc
	v_lshlrev_b32_e32 v81, 2, v2
	v_mul_f32_e32 v2, 0x3e0293ee, v92
	v_exp_f32_e64 v3, -|v2|
	v_cmp_lt_f32_e32 vcc, 0, v2
	v_add_f32_e32 v4, 1.0, v3
	v_rcp_f32_e32 v4, v4
	s_nop 0
	v_mul_f32_e32 v3, v3, v4
	v_cndmask_b32_e32 v2, v3, v4, vcc
	v_cndmask_b32_e32 v3, v4, v3, vcc
	v_cmp_lt_i32_e32 vcc, v190, v83
	s_nop 1
	v_cndmask_b32_e32 v4, 1.0, v3, vcc
	v_mul_f32_e32 v3, 0x3e0293ee, v93
	v_exp_f32_e64 v5, -|v3|
	v_cndmask_b32_e32 v2, 0, v2, vcc
	v_cmp_lt_f32_e32 vcc, 0, v3
	v_mov_b32_e32 v3, s27
	v_add_f32_e32 v6, 1.0, v5
	v_rcp_f32_e32 v6, v6
	s_nop 0
	v_mul_f32_e32 v5, v5, v6
	v_cndmask_b32_e32 v7, v5, v6, vcc
	v_cndmask_b32_e32 v5, v6, v5, vcc
	v_cmp_lt_i32_e32 vcc, v191, v83
	s_nop 1
	v_cndmask_b32_e32 v6, 1.0, v5, vcc
	v_mul_f32_e32 v5, v4, v6
	v_mul_f32_e32 v4, 0x3e0293ee, v94
	v_cndmask_b32_e32 v3, v3, v7, vcc
	v_exp_f32_e64 v7, -|v4|
	v_cmp_lt_f32_e32 vcc, 0, v4
	v_mov_b32_e32 v4, s27
	v_add_f32_e32 v8, 1.0, v7
	v_rcp_f32_e32 v8, v8
	s_nop 0
	v_mul_f32_e32 v7, v7, v8
	v_cndmask_b32_e32 v9, v7, v8, vcc
	v_cndmask_b32_e32 v7, v8, v7, vcc
	v_cmp_lt_i32_e32 vcc, v192, v83
	s_nop 1
	v_cndmask_b32_e32 v7, 1.0, v7, vcc
	v_mul_f32_e32 v8, v7, v5
	v_mul_f32_e32 v5, 0x3e0293ee, v95
	v_cndmask_b32_e32 v4, v4, v9, vcc
	v_exp_f32_e64 v9, -|v5|
	v_cmp_lt_f32_e32 vcc, 0, v5
	v_mov_b32_e32 v5, s27
	v_add_f32_e32 v10, 1.0, v9
	v_rcp_f32_e32 v10, v10
	s_nop 0
	v_mul_f32_e32 v9, v9, v10
	v_cndmask_b32_e32 v11, v9, v10, vcc
	v_cndmask_b32_e32 v9, v10, v9, vcc
	v_cmp_lt_i32_e32 vcc, v193, v83
	s_nop 1
	v_cndmask_b32_e32 v10, 1.0, v9, vcc
	v_cndmask_b32_e32 v5, v5, v11, vcc
	v_mul_f32_e32 v11, v10, v8
	v_mov_b32_e32 v8, v11
	v_mov_b32_e32 v12, v11
	s_nop 1
	v_permlane32_swap_b32_e32 v12, v8
	v_cndmask_b32_e64 v12, v12, v8, s[36:37]
	s_waitcnt lgkmcnt(0)
	v_cndmask_b32_e64 v8, 1.0, v12, s[36:37]
	v_mul_f32_e32 v9, v153, v8
	v_mul_f32_e32 v8, v10, v9
	v_mul_f32_e32 v10, v11, v12
	v_mul_f32_e32 v89, v153, v10
	v_mul_f32_e32 v10, 0x3e0293ee, v88
	v_exp_f32_e64 v11, -|v10|
	v_cmp_lt_f32_e32 vcc, 0, v10
	v_mov_b32_e32 v10, s27
	v_mul_f32_e32 v7, v7, v8
	v_add_f32_e32 v12, 1.0, v11
	v_rcp_f32_e32 v12, v12
	v_mul_f32_e32 v6, v6, v7
	v_pk_mul_f32 v[2:3], v[2:3], v[6:7]
	v_pk_mul_f32 v[4:5], v[4:5], v[8:9]
	v_mul_f32_e32 v11, v11, v12
	v_cndmask_b32_e32 v13, v11, v12, vcc
	v_cndmask_b32_e32 v11, v12, v11, vcc
	v_cmp_lt_i32_e32 vcc, v194, v83
	s_nop 1
	v_cndmask_b32_e32 v12, 1.0, v11, vcc
	v_exp_f32_e64 v11, -|v209|
	v_cndmask_b32_e32 v10, v10, v13, vcc
	v_cmp_lt_f32_e32 vcc, 0, v209
	v_add_f32_e32 v13, 1.0, v11
	v_rcp_f32_e32 v13, v13
	s_nop 0
	v_mul_f32_e32 v11, v11, v13
	v_cndmask_b32_e32 v14, v11, v13, vcc
	v_cndmask_b32_e32 v13, v13, v11, vcc
	v_cmp_lt_i32_e32 vcc, v195, v83
	v_mov_b32_e32 v11, s27
	s_nop 0
	v_cndmask_b32_e32 v11, v11, v14, vcc
	v_cndmask_b32_e32 v14, 1.0, v13, vcc
	v_mul_f32_e32 v13, v12, v14
	v_mul_f32_e32 v12, 0x3e0293ee, v90
	v_exp_f32_e64 v15, -|v12|
	v_cmp_lt_f32_e32 vcc, 0, v12
	v_mov_b32_e32 v12, s27
	v_add_f32_e32 v91, 1.0, v15
	v_rcp_f32_e32 v91, v91
	s_nop 0
	v_mul_f32_e32 v15, v15, v91
	v_cndmask_b32_e32 v154, v15, v91, vcc
	v_cndmask_b32_e32 v15, v91, v15, vcc
	v_cmp_lt_i32_e32 vcc, v196, v83
	s_nop 1
	v_cndmask_b32_e32 v15, 1.0, v15, vcc
	v_mul_f32_e32 v91, v15, v13
	v_exp_f32_e64 v13, -|v152|
	v_cndmask_b32_e32 v12, v12, v154, vcc
	v_cmp_lt_f32_e32 vcc, 0, v152
	v_add_f32_e32 v154, 1.0, v13
	v_rcp_f32_e32 v154, v154
	s_nop 0
	v_mul_f32_e32 v13, v13, v154
	v_cndmask_b32_e32 v155, v13, v154, vcc
	v_cndmask_b32_e32 v154, v154, v13, vcc
	v_cmp_lt_i32_e32 vcc, v197, v83
	v_mov_b32_e32 v13, s27
	s_nop 0
	v_cndmask_b32_e32 v154, 1.0, v154, vcc
	v_mul_f32_e32 v91, v154, v91
	v_mov_b32_e32 v6, v91
	v_mov_b32_e32 v156, v91
	s_nop 1
	v_permlane32_swap_b32_e32 v156, v6
	v_cndmask_b32_e64 v156, v156, v6, s[36:37]
	v_cndmask_b32_e32 v13, v13, v155, vcc
	s_waitcnt lgkmcnt(0)
	v_cndmask_b32_e64 v155, 1.0, v156, s[36:37]
	v_mul_f32_e32 v91, v91, v156
	v_mul_f32_e32 v155, v89, v155
	v_mul_f32_e32 v91, v91, v89
	v_mul_f32_e32 v89, 0x3e0293ee, v84
	v_exp_f32_e64 v156, -|v89|
	v_cmp_lt_f32_e32 vcc, 0, v89
	v_mul_f32_e32 v154, v154, v155
	v_mul_f32_e32 v15, v15, v154
	v_add_f32_e32 v157, 1.0, v156
	v_rcp_f32_e32 v157, v157
	v_mul_f32_e32 v14, v14, v15
	v_pk_mul_f32 v[12:13], v[12:13], v[154:155]
	v_pk_mul_f32 v[10:11], v[10:11], v[14:15]
	v_mul_f32_e32 v156, v156, v157
	v_cndmask_b32_e32 v89, v156, v157, vcc
	v_cndmask_b32_e32 v157, v157, v156, vcc
	v_cmp_lt_i32_e32 vcc, v198, v83
	v_mov_b32_e32 v156, s27
	s_nop 0
	v_cndmask_b32_e32 v156, v156, v89, vcc
	v_mul_f32_e32 v89, 0x3e0293ee, v85
	v_cndmask_b32_e32 v158, 1.0, v157, vcc
	v_exp_f32_e64 v157, -|v89|
	v_cmp_lt_f32_e32 vcc, 0, v89
	v_mov_b32_e32 v89, s27
	v_add_f32_e32 v159, 1.0, v157
	v_rcp_f32_e32 v159, v159
	s_nop 0
	v_mul_f32_e32 v157, v157, v159
	v_cndmask_b32_e32 v160, v157, v159, vcc
	v_cndmask_b32_e32 v159, v159, v157, vcc
	v_cmp_lt_i32_e32 vcc, v199, v83
	s_nop 1
	v_cndmask_b32_e32 v157, v89, v160, vcc
	v_cndmask_b32_e32 v160, 1.0, v159, vcc
	v_mul_f32_e32 v89, v158, v160
	v_mul_f32_e32 v158, 0x3e0293ee, v86
	v_exp_f32_e64 v159, -|v158|
	v_cmp_lt_f32_e32 vcc, 0, v158
	v_mov_b32_e32 v158, s27
	v_add_f32_e32 v161, 1.0, v159
	v_rcp_f32_e32 v161, v161
	s_nop 0
	v_mul_f32_e32 v159, v159, v161
	v_cndmask_b32_e32 v162, v159, v161, vcc
	v_cndmask_b32_e32 v159, v161, v159, vcc
	v_cmp_lt_i32_e32 vcc, v200, v83
	s_nop 1
	v_cndmask_b32_e32 v161, 1.0, v159, vcc
	v_cndmask_b32_e32 v158, v158, v162, vcc
	v_mul_f32_e32 v162, v161, v89
	v_mul_f32_e32 v89, 0x3e0293ee, v87
	v_exp_f32_e64 v159, -|v89|
	v_cmp_lt_f32_e32 vcc, 0, v89
	v_mov_b32_e32 v89, s27
	v_add_f32_e32 v163, 1.0, v159
	v_rcp_f32_e32 v163, v163
	s_nop 0
	v_mul_f32_e32 v159, v159, v163
	v_cndmask_b32_e32 v164, v159, v163, vcc
	v_cndmask_b32_e32 v163, v163, v159, vcc
	v_cmp_lt_i32_e32 vcc, v201, v83
	s_nop 1
	v_cndmask_b32_e32 v159, v89, v164, vcc
	v_cndmask_b32_e32 v89, 1.0, v163, vcc
	v_mul_f32_e32 v164, v89, v162
	v_mov_b32_e32 v6, v164
	v_mov_b32_e32 v165, v164
	s_nop 1
	v_permlane32_swap_b32_e32 v165, v6
	v_cndmask_b32_e64 v165, v165, v6, s[36:37]
	s_waitcnt lgkmcnt(0)
	v_cndmask_b32_e64 v162, 1.0, v165, s[36:37]
	v_mul_f32_e32 v163, v91, v162
	v_mul_f32_e32 v162, v89, v163
	v_mul_f32_e32 v89, v164, v165
	v_mul_f32_e32 v91, v89, v91
	v_mul_f32_e32 v89, 0x3e0293ee, v80
	v_exp_f32_e64 v164, -|v89|
	v_cmp_lt_f32_e32 vcc, 0, v89
	v_mul_f32_e32 v161, v161, v162
	v_mul_f32_e32 v160, v160, v161
	v_add_f32_e32 v165, 1.0, v164
	v_rcp_f32_e32 v165, v165
	v_pk_mul_f32 v[158:159], v[158:159], v[162:163]
	v_pk_mul_f32 v[156:157], v[156:157], v[160:161]
	v_mul_f32_e32 v164, v164, v165
	v_cndmask_b32_e32 v89, v164, v165, vcc
	v_cndmask_b32_e32 v165, v165, v164, vcc
	v_cmp_lt_i32_e32 vcc, v186, v83
	v_mov_b32_e32 v164, s27
	s_nop 0
	v_cndmask_b32_e32 v164, v164, v89, vcc
	v_exp_f32_e64 v89, -|v208|
	v_cndmask_b32_e32 v178, 1.0, v165, vcc
	v_cmp_lt_f32_e32 vcc, 0, v208
	v_add_f32_e32 v165, 1.0, v89
	v_rcp_f32_e32 v165, v165
	s_nop 0
	v_mul_f32_e32 v89, v89, v165
	v_cndmask_b32_e32 v179, v89, v165, vcc
	v_cndmask_b32_e32 v222, v165, v89, vcc
	v_cmp_lt_i32_e32 vcc, v202, v83
	v_mov_b32_e32 v89, s27
	s_nop 0
	v_cndmask_b32_e32 v165, v89, v179, vcc
	v_cndmask_b32_e32 v89, 1.0, v222, vcc
	v_mul_f32_e32 v179, v178, v89
	v_mul_f32_e32 v178, 0x3e0293ee, v82
	v_exp_f32_e64 v222, -|v178|
	v_cmp_lt_f32_e32 vcc, 0, v178
	v_mov_b32_e32 v178, s27
	v_add_f32_e32 v223, 1.0, v222
	v_rcp_f32_e32 v223, v223
	s_nop 0
	v_mul_f32_e32 v222, v222, v223
	v_cndmask_b32_e32 v224, v222, v223, vcc
	v_cndmask_b32_e32 v222, v223, v222, vcc
	v_cmp_lt_i32_e32 vcc, v203, v83
	s_nop 1
	v_cndmask_b32_e32 v178, v178, v224, vcc
	v_cndmask_b32_e32 v224, 1.0, v222, vcc
	v_mul_f32_e32 v222, v224, v179
	v_exp_f32_e64 v179, -|v207|
	v_cmp_lt_f32_e32 vcc, 0, v207
	v_add_f32_e32 v223, 1.0, v179
	v_rcp_f32_e32 v223, v223
	s_nop 0
	v_mul_f32_e32 v179, v179, v223
	v_cndmask_b32_e32 v225, v179, v223, vcc
	v_cndmask_b32_e32 v223, v223, v179, vcc
	v_cmp_lt_i32_e32 vcc, v204, v83
	v_mov_b32_e32 v83, s27
	s_nop 0
	v_cndmask_b32_e32 v179, v83, v225, vcc
	v_cndmask_b32_e32 v83, 1.0, v223, vcc
	v_mul_f32_e32 v226, v83, v222
	v_mov_b32_e32 v6, v226
	v_mov_b32_e32 v81, v226
	s_nop 1
	v_permlane32_swap_b32_e32 v81, v6
	v_cndmask_b32_e64 v81, v81, v6, s[36:37]
	s_waitcnt lgkmcnt(0)
	v_cndmask_b32_e64 v222, 1.0, v81, s[36:37]
	v_mul_f32_e32 v223, v91, v222
	v_mul_f32_e32 v222, v83, v223
	v_mul_f32_e32 v225, v224, v222
	v_mul_f32_e32 v224, v89, v225
	v_mul_f32_e32 v6, v226, v81
	v_pk_mul_f32 v[178:179], v[178:179], v[222:223]
	v_pk_mul_f32 v[164:165], v[164:165], v[224:225]
	v_mul_f32_e32 v6, v6, v91
.LBB0_544:
	s_andn2_b64 vcc, exec, s[0:1]
	s_cbranch_vccnz .LBB0_546
	v_and_b32_e32 v3, 64, v217
	v_xor_b32_e32 v2, 32, v217
	v_add_u32_e32 v3, 64, v3
	v_exp_f32_e64 v81, -|v209|
	v_cmp_lt_i32_e32 vcc, v2, v3
	v_mov_b32_e32 v89, v94
	v_mov_b32_e32 v91, v95
	v_cndmask_b32_e32 v2, v217, v2, vcc
	v_lshlrev_b32_e32 v160, 2, v2
	v_pk_mul_f32 v[2:3], v[88:89], s[34:35] op_sel_hi:[1,0]
	v_add_f32_e32 v4, 1.0, v81
	v_exp_f32_e64 v5, -|v3|
	v_rcp_f32_e32 v83, v4
	v_exp_f32_e64 v4, -|v2|
	v_pk_mul_f32 v[8:9], v[90:91], s[34:35] op_sel_hi:[1,0]
	v_add_f32_e32 v6, 1.0, v5
	v_rcp_f32_e32 v7, v6
	v_add_f32_e32 v6, 1.0, v4
	v_rcp_f32_e32 v6, v6
	v_exp_f32_e64 v11, -|v9|
	v_exp_f32_e64 v10, -|v8|
	v_cmp_lt_f32_e32 vcc, 0, v3
	v_pk_mul_f32 v[14:15], v[4:5], v[6:7]
	v_pk_mul_f32 v[4:5], v[92:93], s[34:35] op_sel_hi:[1,0]
	v_add_f32_e32 v12, 1.0, v11
	v_exp_f32_e64 v88, -|v4|
	v_exp_f32_e64 v89, -|v5|
	v_cndmask_b32_e32 v155, v15, v7, vcc
	v_cndmask_b32_e32 v3, v7, v15, vcc
	v_add_f32_e32 v7, 1.0, v88
	v_rcp_f32_e32 v13, v12
	v_add_f32_e32 v12, 1.0, v10
	v_rcp_f32_e32 v90, v7
	v_add_f32_e32 v7, 1.0, v89
	v_rcp_f32_e32 v12, v12
	v_rcp_f32_e32 v91, v7
	v_cmp_lt_f32_e64 s[0:1], 0, v9
	v_cmp_lt_f32_e64 s[46:47], 0, v5
	v_pk_mul_f32 v[10:11], v[10:11], v[12:13]
	v_pk_mul_f32 v[88:89], v[88:89], v[90:91]
	v_cmp_lt_f32_e64 s[48:49], 0, v4
	v_cndmask_b32_e64 v156, v11, v13, s[0:1]
	v_cmp_lt_f32_e32 vcc, 0, v2
	v_cndmask_b32_e64 v9, v13, v11, s[0:1]
	v_mul_f32_e32 v7, v81, v83
	v_cmp_lt_f32_e64 s[44:45], 0, v209
	v_cndmask_b32_e64 v11, v91, v89, s[46:47]
	v_cndmask_b32_e64 v4, v90, v88, s[48:49]
	v_cndmask_b32_e32 v2, v6, v14, vcc
	v_cmp_lt_f32_e64 s[0:1], 0, v8
	v_cndmask_b32_e64 v92, v83, v7, s[44:45]
	v_mul_f32_e32 v93, v4, v11
	v_exp_f32_e64 v154, -|v152|
	v_cndmask_b32_e64 v8, v12, v10, s[0:1]
	v_pk_mul_f32 v[4:5], v[2:3], v[92:93]
	v_cndmask_b32_e64 v95, v89, v91, s[46:47]
	v_cndmask_b32_e64 v94, v88, v90, s[48:49]
	v_pk_mul_f32 v[88:89], v[8:9], v[4:5]
	v_mov_b32_e32 v2, v89
	v_mov_b32_e32 v91, v89
	s_nop 1
	v_permlane32_swap_b32_e32 v91, v2
	v_cndmask_b32_e64 v91, v91, v2, s[36:37]
	v_add_f32_e32 v2, 1.0, v154
	v_rcp_f32_e32 v13, v2
	v_cmp_lt_f32_e64 s[46:47], 0, v152
	v_cndmask_b32_e32 v6, v14, v6, vcc
	s_waitcnt lgkmcnt(0)
	v_cndmask_b32_e64 v2, 1.0, v91, s[36:37]
	v_mul_f32_e32 v2, v153, v2
	v_mul_f32_e32 v5, v156, v2
	v_mul_f32_e32 v2, v9, v2
	v_mul_f32_e32 v9, v154, v13
	v_cndmask_b32_e64 v90, v13, v9, s[46:47]
	v_pk_mul_f32 v[88:89], v[90:91], v[88:89]
	v_mov_b32_e32 v4, v88
	v_mov_b32_e32 v152, v88
	s_nop 1
	v_permlane32_swap_b32_e32 v152, v4
	v_cndmask_b32_e64 v152, v152, v4, s[36:37]
	v_mul_f32_e32 v3, v3, v2
	v_mul_f32_e32 v4, v155, v2
	v_mul_f32_e32 v2, v11, v3
	v_cndmask_b32_e64 v11, v9, v13, s[46:47]
	s_waitcnt lgkmcnt(0)
	v_cndmask_b32_e64 v9, 1.0, v152, s[36:37]
	v_pk_mul_f32 v[14:15], v[88:89], v[152:153]
	v_cndmask_b32_e64 v10, v10, v12, s[0:1]
	v_mul_f32_e32 v89, v15, v9
	v_mul_f32_e32 v88, v90, v89
	v_mov_b32_e32 v81, v86
	v_exp_f32_e64 v152, -|v208|
	v_pk_mul_f32 v[12:13], v[10:11], v[88:89]
	v_pk_mul_f32 v[10:11], v[80:81], s[34:35] op_sel_hi:[1,0]
	v_cndmask_b32_e64 v7, v7, v83, s[44:45]
	v_exp_f32_e64 v81, -|v11|
	v_exp_f32_e64 v80, -|v10|
	v_add_f32_e32 v83, 1.0, v152
	v_mul_f32_e32 v9, v8, v88
	v_rcp_f32_e32 v161, v83
	v_add_f32_e32 v83, 1.0, v81
	v_add_f32_e32 v88, 1.0, v80
	v_rcp_f32_e32 v89, v83
	v_rcp_f32_e32 v88, v88
	v_mov_b32_e32 v83, v87
	v_cmp_lt_f32_e32 vcc, 0, v11
	v_pk_mul_f32 v[82:83], v[82:83], s[34:35] op_sel_hi:[1,0]
	v_pk_mul_f32 v[80:81], v[80:81], v[88:89]
	v_exp_f32_e64 v87, -|v83|
	v_cndmask_b32_e32 v156, v81, v89, vcc
	v_cndmask_b32_e32 v93, v89, v81, vcc
	v_cmp_lt_f32_e32 vcc, 0, v10
	v_pk_mul_f32 v[10:11], v[84:85], s[34:35] op_sel_hi:[1,0]
	v_exp_f32_e64 v86, -|v82|
	v_exp_f32_e64 v84, -|v10|
	v_exp_f32_e64 v85, -|v11|
	v_add_f32_e32 v90, 1.0, v87
	v_pk_mul_f32 v[2:3], v[94:95], v[2:3]
	v_add_f32_e32 v81, 1.0, v84
	v_rcp_f32_e32 v91, v90
	v_add_f32_e32 v90, 1.0, v86
	v_rcp_f32_e32 v94, v81
	v_add_f32_e32 v81, 1.0, v85
	v_rcp_f32_e32 v90, v90
	v_rcp_f32_e32 v95, v81
	v_cmp_lt_f32_e64 s[0:1], 0, v83
	v_cmp_lt_f32_e64 s[46:47], 0, v11
	v_pk_mul_f32 v[86:87], v[86:87], v[90:91]
	v_pk_mul_f32 v[84:85], v[84:85], v[94:95]
	v_cmp_lt_f32_e64 s[48:49], 0, v10
	v_cndmask_b32_e64 v157, v87, v91, s[0:1]
	v_cndmask_b32_e64 v83, v91, v87, s[0:1]
	v_mul_f32_e32 v81, v152, v161
	v_cmp_lt_f32_e64 s[44:45], 0, v208
	v_cndmask_b32_e64 v87, v95, v85, s[46:47]
	v_cndmask_b32_e64 v10, v94, v84, s[48:49]
	v_mul_f32_e32 v8, v92, v9
	v_cndmask_b32_e32 v92, v88, v80, vcc
	v_cmp_lt_f32_e64 s[0:1], 0, v82
	v_cndmask_b32_e64 v152, v161, v81, s[44:45]
	v_mul_f32_e32 v153, v10, v87
	v_cndmask_b32_e64 v82, v90, v86, s[0:1]
	v_pk_mul_f32 v[10:11], v[92:93], v[152:153]
	v_exp_f32_e64 v162, -|v207|
	v_cndmask_b32_e64 v155, v85, v95, s[46:47]
	v_cndmask_b32_e64 v154, v84, v94, s[48:49]
	v_pk_mul_f32 v[84:85], v[82:83], v[10:11]
	v_mov_b32_e32 v10, v85
	v_mov_b32_e32 v95, v85
	s_nop 1
	v_permlane32_swap_b32_e32 v95, v10
	v_cndmask_b32_e64 v95, v95, v10, s[36:37]
	v_pk_mul_f32 v[10:11], v[6:7], v[8:9]
	v_pk_mul_f32 v[6:7], v[14:15], v[14:15] op_sel:[0,1] op_sel_hi:[1,0]
	v_cmp_lt_f32_e64 s[46:47], 0, v207
	v_add_f32_e32 v7, 1.0, v162
	v_rcp_f32_e32 v7, v7
	s_waitcnt lgkmcnt(0)
	v_cndmask_b32_e64 v8, 1.0, v95, s[36:37]
	v_mul_f32_e32 v8, v6, v8
	v_mul_f32_e32 v159, v157, v8
	v_mul_f32_e32 v8, v83, v8
	v_mul_f32_e32 v9, v93, v8
	v_mul_f32_e32 v15, v162, v7
	v_mul_f32_e32 v158, v156, v8
	v_mul_f32_e32 v8, v87, v9
	v_cndmask_b32_e64 v94, v7, v15, s[46:47]
	v_pk_mul_f32 v[156:157], v[154:155], v[8:9]
	v_pk_mul_f32 v[8:9], v[94:95], v[84:85]
	v_mov_b32_e32 v160, v8
	v_mov_b32_e32 v14, v8
	s_nop 1
	v_permlane32_swap_b32_e32 v14, v160
	v_cndmask_b32_e64 v14, v14, v160, s[36:37]
	v_cndmask_b32_e64 v85, v15, v7, s[46:47]
	v_mov_b32_e32 v15, v6
	v_cndmask_b32_e64 v84, v86, v90, s[0:1]
	v_cndmask_b32_e32 v80, v80, v88, vcc
	s_waitcnt lgkmcnt(0)
	v_cndmask_b32_e64 v83, 1.0, v14, s[36:37]
	v_pk_mul_f32 v[6:7], v[8:9], v[14:15]
	v_cndmask_b32_e64 v81, v81, v161, s[44:45]
	v_mul_f32_e32 v9, v7, v83
	v_mul_f32_e32 v8, v94, v9
	v_pk_mul_f32 v[178:179], v[84:85], v[8:9]
	v_mul_f32_e32 v9, v82, v8
	v_mul_f32_e32 v8, v152, v9
	v_pk_mul_f32 v[164:165], v[80:81], v[8:9]
	v_mul_f32_e32 v6, v6, v7

.LBB0_547:
	v_cmp_gt_f32_e32 vcc, s86, v153
	s_cmp_eq_u64 vcc, -1
	s_cbranch_scc1 .LBB0_553
	v_add_u32_e32 v10, v206, v1
	ds_read_b128 v[2:5], v10
	ds_read_b128 v[6:9], v10 offset:32
	ds_read_b128 v[222:225], v10 offset:64
	ds_read_b128 v[226:229], v10 offset:96
	ds_read_b128 v[230:233], v10 offset:128
	ds_read_b128 v[234:237], v10 offset:160
	ds_read_b128 v[238:241], v10 offset:192
	ds_read_b128 v[242:245], v10 offset:224
	s_or_b32 s12, s84, 31
	s_mov_b64 s[0:1], -1
	s_cmp_lt_i32 s12, s26
	s_waitcnt lgkmcnt(7)
	v_mfma_f32_32x32x16_bf16 v[80:95], v[2:5], v[96:99], 0
	s_waitcnt lgkmcnt(6)
	v_mfma_f32_32x32x16_bf16 v[80:95], v[6:9], v[100:103], v[80:95]
	s_waitcnt lgkmcnt(5)
	v_mfma_f32_32x32x16_bf16 v[80:95], v[222:225], v[104:107], v[80:95]
	s_waitcnt lgkmcnt(4)
	v_mfma_f32_32x32x16_bf16 v[80:95], v[226:229], v[108:111], v[80:95]
	s_waitcnt lgkmcnt(3)
	v_mfma_f32_32x32x16_bf16 v[80:95], v[230:233], v[112:115], v[80:95]
	s_waitcnt lgkmcnt(2)
	v_mfma_f32_32x32x16_bf16 v[80:95], v[234:237], v[116:119], v[80:95]
	s_waitcnt lgkmcnt(1)
	v_mfma_f32_32x32x16_bf16 v[80:95], v[238:241], v[120:123], v[80:95]
	s_waitcnt lgkmcnt(0)
	v_mfma_f32_32x32x16_bf16 v[80:95], v[242:245], v[124:127], v[80:95]
	s_nop 11
	v_mul_f32_e32 v208, 0x3e0293ee, v89
	v_mul_f32_e32 v152, 0x3e0293ee, v91
	v_mul_f32_e32 v207, 0x3e0293ee, v81
	v_mul_f32_e32 v206, 0x3e0293ee, v83
	s_cbranch_scc1 .LBB0_550
	v_and_b32_e32 v3, 64, v217
	v_xor_b32_e32 v2, 32, v217
	v_add_u32_e32 v3, 64, v3
	v_cmp_lt_i32_e32 vcc, v2, v3
	v_subrev_u32_e32 v83, s84, v185
	s_mov_b64 s[0:1], 0
	v_cndmask_b32_e32 v2, v217, v2, vcc
	v_lshlrev_b32_e32 v81, 2, v2
	v_mul_f32_e32 v2, 0x3e0293ee, v92
	v_exp_f32_e64 v3, -|v2|
	v_cmp_lt_f32_e32 vcc, 0, v2
	v_add_f32_e32 v4, 1.0, v3
	v_rcp_f32_e32 v4, v4
	s_nop 0
	v_mul_f32_e32 v3, v3, v4
	v_cndmask_b32_e32 v2, v3, v4, vcc
	v_cndmask_b32_e32 v3, v4, v3, vcc
	v_cmp_lt_i32_e32 vcc, v190, v83
	s_nop 1
	v_cndmask_b32_e32 v4, 1.0, v3, vcc
	v_mul_f32_e32 v3, 0x3e0293ee, v93
	v_exp_f32_e64 v5, -|v3|
	v_cndmask_b32_e32 v2, 0, v2, vcc
	v_cmp_lt_f32_e32 vcc, 0, v3
	v_mov_b32_e32 v3, s27
	v_add_f32_e32 v6, 1.0, v5
	v_rcp_f32_e32 v6, v6
	s_nop 0
	v_mul_f32_e32 v5, v5, v6
	v_cndmask_b32_e32 v7, v5, v6, vcc
	v_cndmask_b32_e32 v5, v6, v5, vcc
	v_cmp_lt_i32_e32 vcc, v191, v83
	s_nop 1
	v_cndmask_b32_e32 v6, 1.0, v5, vcc
	v_mul_f32_e32 v5, v4, v6
	v_mul_f32_e32 v4, 0x3e0293ee, v94
	v_cndmask_b32_e32 v3, v3, v7, vcc
	v_exp_f32_e64 v7, -|v4|
	v_cmp_lt_f32_e32 vcc, 0, v4
	v_mov_b32_e32 v4, s27
	v_add_f32_e32 v8, 1.0, v7
	v_rcp_f32_e32 v8, v8
	s_nop 0
	v_mul_f32_e32 v7, v7, v8
	v_cndmask_b32_e32 v9, v7, v8, vcc
	v_cndmask_b32_e32 v7, v8, v7, vcc
	v_cmp_lt_i32_e32 vcc, v192, v83
	s_nop 1
	v_cndmask_b32_e32 v7, 1.0, v7, vcc
	v_mul_f32_e32 v8, v7, v5
	v_mul_f32_e32 v5, 0x3e0293ee, v95
	v_cndmask_b32_e32 v4, v4, v9, vcc
	v_exp_f32_e64 v9, -|v5|
	v_cmp_lt_f32_e32 vcc, 0, v5
	v_mov_b32_e32 v5, s27
	v_add_f32_e32 v10, 1.0, v9
	v_rcp_f32_e32 v10, v10
	s_nop 0
	v_mul_f32_e32 v9, v9, v10
	v_cndmask_b32_e32 v11, v9, v10, vcc
	v_cndmask_b32_e32 v9, v10, v9, vcc
	v_cmp_lt_i32_e32 vcc, v193, v83
	s_nop 1
	v_cndmask_b32_e32 v10, 1.0, v9, vcc
	v_cndmask_b32_e32 v5, v5, v11, vcc
	v_mul_f32_e32 v11, v10, v8
	v_mov_b32_e32 v8, v11
	v_mov_b32_e32 v12, v11
	s_nop 1
	v_permlane32_swap_b32_e32 v12, v8
	v_cndmask_b32_e64 v12, v12, v8, s[36:37]
	s_waitcnt lgkmcnt(0)
	v_cndmask_b32_e64 v8, 1.0, v12, s[36:37]
	v_mul_f32_e32 v9, v153, v8
	v_mul_f32_e32 v8, v10, v9
	v_mul_f32_e32 v10, v11, v12
	v_mul_f32_e32 v89, v153, v10
	v_mul_f32_e32 v10, 0x3e0293ee, v88
	v_exp_f32_e64 v11, -|v10|
	v_cmp_lt_f32_e32 vcc, 0, v10
	v_mov_b32_e32 v10, s27
	v_mul_f32_e32 v7, v7, v8
	v_add_f32_e32 v12, 1.0, v11
	v_rcp_f32_e32 v12, v12
	v_mul_f32_e32 v6, v6, v7
	v_pk_mul_f32 v[2:3], v[2:3], v[6:7]
	v_pk_mul_f32 v[4:5], v[4:5], v[8:9]
	v_mul_f32_e32 v11, v11, v12
	v_cndmask_b32_e32 v13, v11, v12, vcc
	v_cndmask_b32_e32 v11, v12, v11, vcc
	v_cmp_lt_i32_e32 vcc, v194, v83
	s_nop 1
	v_cndmask_b32_e32 v12, 1.0, v11, vcc
	v_exp_f32_e64 v11, -|v208|
	v_cndmask_b32_e32 v10, v10, v13, vcc
	v_cmp_lt_f32_e32 vcc, 0, v208
	v_add_f32_e32 v13, 1.0, v11
	v_rcp_f32_e32 v13, v13
	s_nop 0
	v_mul_f32_e32 v11, v11, v13
	v_cndmask_b32_e32 v14, v11, v13, vcc
	v_cndmask_b32_e32 v13, v13, v11, vcc
	v_cmp_lt_i32_e32 vcc, v195, v83
	v_mov_b32_e32 v11, s27
	s_nop 0
	v_cndmask_b32_e32 v11, v11, v14, vcc
	v_cndmask_b32_e32 v14, 1.0, v13, vcc
	v_mul_f32_e32 v13, v12, v14
	v_mul_f32_e32 v12, 0x3e0293ee, v90
	v_exp_f32_e64 v15, -|v12|
	v_cmp_lt_f32_e32 vcc, 0, v12
	v_mov_b32_e32 v12, s27
	v_add_f32_e32 v91, 1.0, v15
	v_rcp_f32_e32 v91, v91
	s_nop 0
	v_mul_f32_e32 v15, v15, v91
	v_cndmask_b32_e32 v154, v15, v91, vcc
	v_cndmask_b32_e32 v15, v91, v15, vcc
	v_cmp_lt_i32_e32 vcc, v196, v83
	s_nop 1
	v_cndmask_b32_e32 v15, 1.0, v15, vcc
	v_mul_f32_e32 v91, v15, v13
	v_exp_f32_e64 v13, -|v152|
	v_cndmask_b32_e32 v12, v12, v154, vcc
	v_cmp_lt_f32_e32 vcc, 0, v152
	v_add_f32_e32 v154, 1.0, v13
	v_rcp_f32_e32 v154, v154
	s_nop 0
	v_mul_f32_e32 v13, v13, v154
	v_cndmask_b32_e32 v155, v13, v154, vcc
	v_cndmask_b32_e32 v154, v154, v13, vcc
	v_cmp_lt_i32_e32 vcc, v197, v83
	v_mov_b32_e32 v13, s27
	s_nop 0
	v_cndmask_b32_e32 v154, 1.0, v154, vcc
	v_mul_f32_e32 v91, v154, v91
	v_mov_b32_e32 v6, v91
	v_mov_b32_e32 v156, v91
	s_nop 1
	v_permlane32_swap_b32_e32 v156, v6
	v_cndmask_b32_e64 v156, v156, v6, s[36:37]
	v_cndmask_b32_e32 v13, v13, v155, vcc
	s_waitcnt lgkmcnt(0)
	v_cndmask_b32_e64 v155, 1.0, v156, s[36:37]
	v_mul_f32_e32 v91, v91, v156
	v_mul_f32_e32 v155, v89, v155
	v_mul_f32_e32 v91, v91, v89
	v_mul_f32_e32 v89, 0x3e0293ee, v84
	v_exp_f32_e64 v156, -|v89|
	v_cmp_lt_f32_e32 vcc, 0, v89
	v_mul_f32_e32 v154, v154, v155
	v_mul_f32_e32 v15, v15, v154
	v_add_f32_e32 v157, 1.0, v156
	v_rcp_f32_e32 v157, v157
	v_mul_f32_e32 v14, v14, v15
	v_pk_mul_f32 v[12:13], v[12:13], v[154:155]
	v_pk_mul_f32 v[10:11], v[10:11], v[14:15]
	v_mul_f32_e32 v156, v156, v157
	v_cndmask_b32_e32 v89, v156, v157, vcc
	v_cndmask_b32_e32 v157, v157, v156, vcc
	v_cmp_lt_i32_e32 vcc, v198, v83
	v_mov_b32_e32 v156, s27
	s_nop 0
	v_cndmask_b32_e32 v156, v156, v89, vcc
	v_mul_f32_e32 v89, 0x3e0293ee, v85
	v_cndmask_b32_e32 v158, 1.0, v157, vcc
	v_exp_f32_e64 v157, -|v89|
	v_cmp_lt_f32_e32 vcc, 0, v89
	v_mov_b32_e32 v89, s27
	v_add_f32_e32 v159, 1.0, v157
	v_rcp_f32_e32 v159, v159
	s_nop 0
	v_mul_f32_e32 v157, v157, v159
	v_cndmask_b32_e32 v160, v157, v159, vcc
	v_cndmask_b32_e32 v159, v159, v157, vcc
	v_cmp_lt_i32_e32 vcc, v199, v83
	s_nop 1
	v_cndmask_b32_e32 v157, v89, v160, vcc
	v_cndmask_b32_e32 v160, 1.0, v159, vcc
	v_mul_f32_e32 v89, v158, v160
	v_mul_f32_e32 v158, 0x3e0293ee, v86
	v_exp_f32_e64 v159, -|v158|
	v_cmp_lt_f32_e32 vcc, 0, v158
	v_mov_b32_e32 v158, s27
	v_add_f32_e32 v161, 1.0, v159
	v_rcp_f32_e32 v161, v161
	s_nop 0
	v_mul_f32_e32 v159, v159, v161
	v_cndmask_b32_e32 v162, v159, v161, vcc
	v_cndmask_b32_e32 v159, v161, v159, vcc
	v_cmp_lt_i32_e32 vcc, v200, v83
	s_nop 1
	v_cndmask_b32_e32 v161, 1.0, v159, vcc
	v_cndmask_b32_e32 v158, v158, v162, vcc
	v_mul_f32_e32 v162, v161, v89
	v_mul_f32_e32 v89, 0x3e0293ee, v87
	v_exp_f32_e64 v159, -|v89|
	v_cmp_lt_f32_e32 vcc, 0, v89
	v_mov_b32_e32 v89, s27
	v_add_f32_e32 v163, 1.0, v159
	v_rcp_f32_e32 v163, v163
	s_nop 0
	v_mul_f32_e32 v159, v159, v163
	v_cndmask_b32_e32 v164, v159, v163, vcc
	v_cndmask_b32_e32 v163, v163, v159, vcc
	v_cmp_lt_i32_e32 vcc, v201, v83
	s_nop 1
	v_cndmask_b32_e32 v159, v89, v164, vcc
	v_cndmask_b32_e32 v89, 1.0, v163, vcc
	v_mul_f32_e32 v164, v89, v162
	v_mov_b32_e32 v6, v164
	v_mov_b32_e32 v165, v164
	s_nop 1
	v_permlane32_swap_b32_e32 v165, v6
	v_cndmask_b32_e64 v165, v165, v6, s[36:37]
	s_waitcnt lgkmcnt(0)
	v_cndmask_b32_e64 v162, 1.0, v165, s[36:37]
	v_mul_f32_e32 v163, v91, v162
	v_mul_f32_e32 v162, v89, v163
	v_mul_f32_e32 v89, v164, v165
	v_mul_f32_e32 v91, v89, v91
	v_mul_f32_e32 v89, 0x3e0293ee, v80
	v_exp_f32_e64 v164, -|v89|
	v_cmp_lt_f32_e32 vcc, 0, v89
	v_mul_f32_e32 v161, v161, v162
	v_mul_f32_e32 v160, v160, v161
	v_add_f32_e32 v165, 1.0, v164
	v_rcp_f32_e32 v165, v165
	v_pk_mul_f32 v[158:159], v[158:159], v[162:163]
	v_pk_mul_f32 v[156:157], v[156:157], v[160:161]
	v_mul_f32_e32 v164, v164, v165
	v_cndmask_b32_e32 v89, v164, v165, vcc
	v_cndmask_b32_e32 v165, v165, v164, vcc
	v_cmp_lt_i32_e32 vcc, v186, v83
	v_mov_b32_e32 v164, s27
	s_nop 0
	v_cndmask_b32_e32 v164, v164, v89, vcc
	v_exp_f32_e64 v89, -|v207|
	v_cndmask_b32_e32 v178, 1.0, v165, vcc
	v_cmp_lt_f32_e32 vcc, 0, v207
	v_add_f32_e32 v165, 1.0, v89
	v_rcp_f32_e32 v165, v165
	s_nop 0
	v_mul_f32_e32 v89, v89, v165
	v_cndmask_b32_e32 v179, v89, v165, vcc
	v_cndmask_b32_e32 v209, v165, v89, vcc
	v_cmp_lt_i32_e32 vcc, v202, v83
	v_mov_b32_e32 v89, s27
	s_nop 0
	v_cndmask_b32_e32 v165, v89, v179, vcc
	v_cndmask_b32_e32 v89, 1.0, v209, vcc
	v_mul_f32_e32 v179, v178, v89
	v_mul_f32_e32 v178, 0x3e0293ee, v82
	v_exp_f32_e64 v209, -|v178|
	v_cmp_lt_f32_e32 vcc, 0, v178
	v_mov_b32_e32 v178, s27
	v_add_f32_e32 v222, 1.0, v209
	v_rcp_f32_e32 v222, v222
	s_nop 0
	v_mul_f32_e32 v209, v209, v222
	v_cndmask_b32_e32 v223, v209, v222, vcc
	v_cndmask_b32_e32 v209, v222, v209, vcc
	v_cmp_lt_i32_e32 vcc, v203, v83
	s_nop 1
	v_cndmask_b32_e32 v209, 1.0, v209, vcc
	v_mul_f32_e32 v222, v209, v179
	v_exp_f32_e64 v179, -|v206|
	v_cndmask_b32_e32 v178, v178, v223, vcc
	v_cmp_lt_f32_e32 vcc, 0, v206
	v_add_f32_e32 v223, 1.0, v179
	v_rcp_f32_e32 v223, v223
	s_nop 0
	v_mul_f32_e32 v179, v179, v223
	v_cndmask_b32_e32 v224, v179, v223, vcc
	v_cndmask_b32_e32 v223, v223, v179, vcc
	v_cmp_lt_i32_e32 vcc, v204, v83
	v_mov_b32_e32 v83, s27
	s_nop 0
	v_cndmask_b32_e32 v179, v83, v224, vcc
	v_cndmask_b32_e32 v83, 1.0, v223, vcc
	v_mul_f32_e32 v226, v83, v222
	v_mov_b32_e32 v6, v226
	v_mov_b32_e32 v81, v226
	s_nop 1
	v_permlane32_swap_b32_e32 v81, v6
	v_cndmask_b32_e64 v81, v81, v6, s[36:37]
	s_waitcnt lgkmcnt(0)
	v_cndmask_b32_e64 v222, 1.0, v81, s[36:37]
	v_mul_f32_e32 v223, v91, v222
	v_mul_f32_e32 v222, v83, v223
	v_mul_f32_e32 v225, v209, v222
	v_mul_f32_e32 v224, v89, v225
	v_mul_f32_e32 v6, v226, v81
	v_pk_mul_f32 v[178:179], v[178:179], v[222:223]
	v_pk_mul_f32 v[164:165], v[164:165], v[224:225]
	v_mul_f32_e32 v6, v6, v91
.LBB0_550:
	s_andn2_b64 vcc, exec, s[0:1]
	s_cbranch_vccnz .LBB0_552
	v_and_b32_e32 v3, 64, v217
	v_xor_b32_e32 v2, 32, v217
	v_add_u32_e32 v3, 64, v3
	v_exp_f32_e64 v81, -|v208|
	v_cmp_lt_i32_e32 vcc, v2, v3
	v_mov_b32_e32 v89, v94
	v_mov_b32_e32 v91, v95
	v_cndmask_b32_e32 v2, v217, v2, vcc
	v_lshlrev_b32_e32 v160, 2, v2
	v_pk_mul_f32 v[2:3], v[88:89], s[34:35] op_sel_hi:[1,0]
	v_add_f32_e32 v4, 1.0, v81
	v_exp_f32_e64 v5, -|v3|
	v_rcp_f32_e32 v83, v4
	v_exp_f32_e64 v4, -|v2|
	v_pk_mul_f32 v[8:9], v[90:91], s[34:35] op_sel_hi:[1,0]
	v_add_f32_e32 v6, 1.0, v5
	v_rcp_f32_e32 v7, v6
	v_add_f32_e32 v6, 1.0, v4
	v_rcp_f32_e32 v6, v6
	v_exp_f32_e64 v11, -|v9|
	v_exp_f32_e64 v10, -|v8|
	v_cmp_lt_f32_e32 vcc, 0, v3
	v_pk_mul_f32 v[14:15], v[4:5], v[6:7]
	v_pk_mul_f32 v[4:5], v[92:93], s[34:35] op_sel_hi:[1,0]
	v_add_f32_e32 v12, 1.0, v11
	v_exp_f32_e64 v88, -|v4|
	v_exp_f32_e64 v89, -|v5|
	v_cndmask_b32_e32 v155, v15, v7, vcc
	v_cndmask_b32_e32 v3, v7, v15, vcc
	v_add_f32_e32 v7, 1.0, v88
	v_rcp_f32_e32 v13, v12
	v_add_f32_e32 v12, 1.0, v10
	v_rcp_f32_e32 v90, v7
	v_add_f32_e32 v7, 1.0, v89
	v_rcp_f32_e32 v12, v12
	v_rcp_f32_e32 v91, v7
	v_cmp_lt_f32_e64 s[0:1], 0, v9
	v_cmp_lt_f32_e64 s[46:47], 0, v5
	v_pk_mul_f32 v[10:11], v[10:11], v[12:13]
	v_pk_mul_f32 v[88:89], v[88:89], v[90:91]
	v_cmp_lt_f32_e64 s[48:49], 0, v4
	v_cndmask_b32_e64 v156, v11, v13, s[0:1]
	v_cmp_lt_f32_e32 vcc, 0, v2
	v_cndmask_b32_e64 v9, v13, v11, s[0:1]
	v_mul_f32_e32 v7, v81, v83
	v_cmp_lt_f32_e64 s[44:45], 0, v208
	v_cndmask_b32_e64 v11, v91, v89, s[46:47]
	v_cndmask_b32_e64 v4, v90, v88, s[48:49]
	v_cndmask_b32_e32 v2, v6, v14, vcc
	v_cmp_lt_f32_e64 s[0:1], 0, v8
	v_cndmask_b32_e64 v92, v83, v7, s[44:45]
	v_mul_f32_e32 v93, v4, v11
	v_exp_f32_e64 v154, -|v152|
	v_cndmask_b32_e64 v8, v12, v10, s[0:1]
	v_pk_mul_f32 v[4:5], v[2:3], v[92:93]
	v_cndmask_b32_e64 v95, v89, v91, s[46:47]
	v_cndmask_b32_e64 v94, v88, v90, s[48:49]
	v_pk_mul_f32 v[88:89], v[8:9], v[4:5]
	v_mov_b32_e32 v2, v89
	v_mov_b32_e32 v91, v89
	s_nop 1
	v_permlane32_swap_b32_e32 v91, v2
	v_cndmask_b32_e64 v91, v91, v2, s[36:37]
	v_add_f32_e32 v2, 1.0, v154
	v_rcp_f32_e32 v13, v2
	v_cmp_lt_f32_e64 s[46:47], 0, v152
	v_cndmask_b32_e32 v6, v14, v6, vcc
	s_waitcnt lgkmcnt(0)
	v_cndmask_b32_e64 v2, 1.0, v91, s[36:37]
	v_mul_f32_e32 v2, v153, v2
	v_mul_f32_e32 v5, v156, v2
	v_mul_f32_e32 v2, v9, v2
	v_mul_f32_e32 v9, v154, v13
	v_cndmask_b32_e64 v90, v13, v9, s[46:47]
	v_pk_mul_f32 v[88:89], v[90:91], v[88:89]
	v_mov_b32_e32 v4, v88
	v_mov_b32_e32 v152, v88
	s_nop 1
	v_permlane32_swap_b32_e32 v152, v4
	v_cndmask_b32_e64 v152, v152, v4, s[36:37]
	v_mul_f32_e32 v3, v3, v2
	v_mul_f32_e32 v4, v155, v2
	v_mul_f32_e32 v2, v11, v3
	v_cndmask_b32_e64 v11, v9, v13, s[46:47]
	s_waitcnt lgkmcnt(0)
	v_cndmask_b32_e64 v9, 1.0, v152, s[36:37]
	v_pk_mul_f32 v[14:15], v[88:89], v[152:153]
	v_cndmask_b32_e64 v10, v10, v12, s[0:1]
	v_mul_f32_e32 v89, v15, v9
	v_mul_f32_e32 v88, v90, v89
	v_mov_b32_e32 v81, v86
	v_exp_f32_e64 v152, -|v207|
	v_pk_mul_f32 v[12:13], v[10:11], v[88:89]
	v_pk_mul_f32 v[10:11], v[80:81], s[34:35] op_sel_hi:[1,0]
	v_cndmask_b32_e64 v7, v7, v83, s[44:45]
	v_exp_f32_e64 v81, -|v11|
	v_exp_f32_e64 v80, -|v10|
	v_add_f32_e32 v83, 1.0, v152
	v_mul_f32_e32 v9, v8, v88
	v_rcp_f32_e32 v161, v83
	v_add_f32_e32 v83, 1.0, v81
	v_add_f32_e32 v88, 1.0, v80
	v_rcp_f32_e32 v89, v83
	v_rcp_f32_e32 v88, v88
	v_mov_b32_e32 v83, v87
	v_cmp_lt_f32_e32 vcc, 0, v11
	v_pk_mul_f32 v[82:83], v[82:83], s[34:35] op_sel_hi:[1,0]
	v_pk_mul_f32 v[80:81], v[80:81], v[88:89]
	v_exp_f32_e64 v87, -|v83|
	v_cndmask_b32_e32 v156, v81, v89, vcc
	v_cndmask_b32_e32 v93, v89, v81, vcc
	v_cmp_lt_f32_e32 vcc, 0, v10
	v_pk_mul_f32 v[10:11], v[84:85], s[34:35] op_sel_hi:[1,0]
	v_exp_f32_e64 v86, -|v82|
	v_exp_f32_e64 v84, -|v10|
	v_exp_f32_e64 v85, -|v11|
	v_add_f32_e32 v90, 1.0, v87
	v_pk_mul_f32 v[2:3], v[94:95], v[2:3]
	v_add_f32_e32 v81, 1.0, v84
	v_rcp_f32_e32 v91, v90
	v_add_f32_e32 v90, 1.0, v86
	v_rcp_f32_e32 v94, v81
	v_add_f32_e32 v81, 1.0, v85
	v_rcp_f32_e32 v90, v90
	v_rcp_f32_e32 v95, v81
	v_cmp_lt_f32_e64 s[0:1], 0, v83
	v_cmp_lt_f32_e64 s[46:47], 0, v11
	v_pk_mul_f32 v[86:87], v[86:87], v[90:91]
	v_pk_mul_f32 v[84:85], v[84:85], v[94:95]
	v_cmp_lt_f32_e64 s[48:49], 0, v10
	v_cndmask_b32_e64 v157, v87, v91, s[0:1]
	v_cndmask_b32_e64 v83, v91, v87, s[0:1]
	v_mul_f32_e32 v81, v152, v161
	v_cmp_lt_f32_e64 s[44:45], 0, v207
	v_cndmask_b32_e64 v87, v95, v85, s[46:47]
	v_cndmask_b32_e64 v10, v94, v84, s[48:49]
	v_mul_f32_e32 v8, v92, v9
	v_cndmask_b32_e32 v92, v88, v80, vcc
	v_cmp_lt_f32_e64 s[0:1], 0, v82
	v_cndmask_b32_e64 v152, v161, v81, s[44:45]
	v_mul_f32_e32 v153, v10, v87
	v_cndmask_b32_e64 v82, v90, v86, s[0:1]
	v_pk_mul_f32 v[10:11], v[92:93], v[152:153]
	v_exp_f32_e64 v162, -|v206|
	v_cndmask_b32_e64 v155, v85, v95, s[46:47]
	v_cndmask_b32_e64 v154, v84, v94, s[48:49]
	v_pk_mul_f32 v[84:85], v[82:83], v[10:11]
	v_mov_b32_e32 v10, v85
	v_mov_b32_e32 v95, v85
	s_nop 1
	v_permlane32_swap_b32_e32 v95, v10
	v_cndmask_b32_e64 v95, v95, v10, s[36:37]
	v_pk_mul_f32 v[10:11], v[6:7], v[8:9]
	v_pk_mul_f32 v[6:7], v[14:15], v[14:15] op_sel:[0,1] op_sel_hi:[1,0]
	v_cmp_lt_f32_e64 s[46:47], 0, v206
	v_add_f32_e32 v7, 1.0, v162
	v_rcp_f32_e32 v7, v7
	s_waitcnt lgkmcnt(0)
	v_cndmask_b32_e64 v8, 1.0, v95, s[36:37]
	v_mul_f32_e32 v8, v6, v8
	v_mul_f32_e32 v159, v157, v8
	v_mul_f32_e32 v8, v83, v8
	v_mul_f32_e32 v9, v93, v8
	v_mul_f32_e32 v15, v162, v7
	v_mul_f32_e32 v158, v156, v8
	v_mul_f32_e32 v8, v87, v9
	v_cndmask_b32_e64 v94, v7, v15, s[46:47]
	v_pk_mul_f32 v[156:157], v[154:155], v[8:9]
	v_pk_mul_f32 v[8:9], v[94:95], v[84:85]
	v_mov_b32_e32 v160, v8
	v_mov_b32_e32 v14, v8
	s_nop 1
	v_permlane32_swap_b32_e32 v14, v160
	v_cndmask_b32_e64 v14, v14, v160, s[36:37]
	v_cndmask_b32_e64 v85, v15, v7, s[46:47]
	v_mov_b32_e32 v15, v6
	v_cndmask_b32_e64 v84, v86, v90, s[0:1]
	v_cndmask_b32_e32 v80, v80, v88, vcc
	s_waitcnt lgkmcnt(0)
	v_cndmask_b32_e64 v83, 1.0, v14, s[36:37]
	v_pk_mul_f32 v[6:7], v[8:9], v[14:15]
	v_cndmask_b32_e64 v81, v81, v161, s[44:45]
	v_mul_f32_e32 v9, v7, v83
	v_mul_f32_e32 v8, v94, v9
	v_pk_mul_f32 v[178:179], v[84:85], v[8:9]
	v_mul_f32_e32 v9, v82, v8
	v_mul_f32_e32 v8, v152, v9
	v_pk_mul_f32 v[164:165], v[80:81], v[8:9]
	v_mul_f32_e32 v6, v6, v7
